# code placement: up-GEMM, residual-GEMM and NA window loop heads moved to 32-byte offsets (dead padding only; phase probes -7.5 / -3.6 / -1.5 us); prologue transposes skip workgroups 0-31
# speedup vs baseline: 1.0045x; 1.0045x over previous
; #define PG8_STAGE(bufoff, gbase, voff) do { _Pragma("unroll") for (int _i = 0; _i < 2; ++_i) \
;         __builtin_amdgcn_global_load_lds((const unsigned*)((const char*)(gbase) + (voff)[_i]), (PG8_LAS unsigned*)(lds + (bufoff) + ldsw + _i * 8192), 16, 0, 0); } while (0)
; #define PG8_LDA(dst, b, h) do { _Pragma("unroll") for (int m = 0; m < 4; ++m) _Pragma("unroll") for (int k = 0; k < 2; ++k) dst[m][k] = *(const PG8_LAS bf16x8*)(lds + PG8_SA(b, h) + aoff + m * 2048 + k * 1024); } while (0)
; #define PG8_LDB(dst, b, h) do { _Pragma("unroll") for (int n = 0; n < 2; ++n) _Pragma("unroll") for (int k = 0; k < 2; ++k) dst[n][k] = *(const PG8_LAS bf16x8*)(lds + PG8_SB(b, h) + boff + n * 2048 + k * 1024); } while (0)
; #define PG8_MMA(ai, bj, At, Bt) do { __builtin_amdgcn_s_setprio(1); _Pragma("unroll") for (int m = 0; m < 4; ++m) _Pragma("unroll") for (int n = 0; n < 2; ++n) _Pragma("unroll") for (int k = 0; k < 2; ++k) \
;         acc[ai][bj][m][n] = __builtin_amdgcn_mfma_f32_16x16x32_bf16(Bt[n][k], At[m][k], acc[ai][bj][m][n], 0, 0, 0); __builtin_amdgcn_s_setprio(0); } while (0)
; #define PG8_WAIT_V(n) asm volatile("s_waitcnt vmcnt(" #n ")" ::: "memory")
; #define PG8_WAIT_L(n) asm volatile("s_waitcnt lgkmcnt(" #n ")" ::: "memory")
; #define PG8_BAR __builtin_amdgcn_s_barrier()
; #define PG8_SCHED __builtin_amdgcn_sched_barrier(0)
; template <class Epi, class Sched, bool ALIGN_EPI = false, bool SP2 = false>
; __device__ __forceinline__ void gemm_phase(PG8_LAS unsigned char* lds, const Gemm g, const Sched& S, const Epi& E) {
;     ...
;             PG8_LDB(B0, 0, 0); PG8_LDB(B1, 0, 1); PG8_SCHED; PG8_LDA(At, 0, 0); PG8_STAGE(PG8_SA(1, 1), a1 + hstep, voffA);
;             PG8_WAIT_V(8); PG8_WAIT_L(0); PG8_BAR; PG8_MMA(0, 0, At, B0); PG8_MMA(0, 1, At, B1); PG8_BAR; PG8_SCHED;
;             PG8_LDA(At, 0, 1); PG8_STAGE(PG8_SB(0, 0), b2, voffB); PG8_STAGE(PG8_SB(0, 1), b2 + hstep, voffB); PG8_STAGE(PG8_SA(0, 0), a2, voffA);
;             PG8_WAIT_V(8); PG8_WAIT_L(0); PG8_BAR; PG8_MMA(1, 0, At, B0); PG8_MMA(1, 1, At, B1); PG8_BAR; PG8_SCHED;
.LBB0_163:
	s_add_u32 s34, s30, 0xfffc0080
	s_addc_u32 s35, s31, -1
	s_add_i32 s71, 0, 0x10000
	s_cmp_eq_u32 s62, 12
	s_cselect_b32 s41, s21, s35
	s_cselect_b32 s40, s27, s34
	v_add_u32_e32 v155, s71, v145
	s_cselect_b32 s35, s19, s54
	s_cselect_b32 s34, s50, s52
	s_add_i32 s74, 0, 0x14000
	ds_read_b128 v[156:159], v155
	ds_read_b128 v[160:163], v155 offset:1024
	ds_read_b128 v[164:167], v155 offset:2048
	ds_read_b128 v[168:171], v155 offset:3072
	v_add_u32_e32 v155, s74, v145
	ds_read_b128 v[172:175], v155
	ds_read_b128 v[176:179], v155 offset:1024
	ds_read_b128 v[180:183], v155 offset:2048
	ds_read_b128 v[208:211], v155 offset:3072
	v_lshl_add_u64 v[202:203], s[30:31], 0, v[134:135]
	s_add_i32 m0, s29, 0xc000
	ds_read_b128 v[212:215], v154
	ds_read_b128 v[216:219], v154 offset:1024
	ds_read_b128 v[220:223], v154 offset:2048
	ds_read_b128 v[224:227], v154 offset:3072
	ds_read_b128 v[228:231], v154 offset:4096
	ds_read_b128 v[232:235], v154 offset:5120
	ds_read_b128 v[236:239], v154 offset:6144
	ds_read_b128 v[240:243], v154 offset:7168
	global_load_lds_dwordx4 v[202:203], off
	v_lshl_add_u64 v[202:203], s[30:31], 0, v[136:137]
	s_add_i32 m0, s29, 0xe000
	s_nop 0
	global_load_lds_dwordx4 v[202:203], off
	s_waitcnt vmcnt(8)
	s_waitcnt lgkmcnt(0)
	s_barrier
	s_setprio 1
	s_waitcnt lgkmcnt(0)
	v_mfma_f32_16x16x32_bf16 v[126:129], v[156:159], v[212:215], v[126:129]
	v_mfma_f32_16x16x32_bf16 v[122:125], v[164:167], v[212:215], v[122:125]
	v_mfma_f32_16x16x32_bf16 v[110:113], v[156:159], v[220:223], v[110:113]
	v_mfma_f32_16x16x32_bf16 v[106:109], v[164:167], v[220:223], v[106:109]
	v_mfma_f32_16x16x32_bf16 v[94:97], v[156:159], v[228:231], v[94:97]
	v_mfma_f32_16x16x32_bf16 v[90:93], v[164:167], v[228:231], v[90:93]
	v_mfma_f32_16x16x32_bf16 v[78:81], v[156:159], v[236:239], v[78:81]
	v_mfma_f32_16x16x32_bf16 v[74:77], v[164:167], v[236:239], v[74:77]
	v_mfma_f32_16x16x32_bf16 v[126:129], v[160:163], v[216:219], v[126:129]
	v_mfma_f32_16x16x32_bf16 v[122:125], v[168:171], v[216:219], v[122:125]
	v_mfma_f32_16x16x32_bf16 v[110:113], v[160:163], v[224:227], v[110:113]
	v_mfma_f32_16x16x32_bf16 v[106:109], v[168:171], v[224:227], v[106:109]
	v_mfma_f32_16x16x32_bf16 v[94:97], v[160:163], v[232:235], v[94:97]
	v_mfma_f32_16x16x32_bf16 v[90:93], v[168:171], v[232:235], v[90:93]
	v_mfma_f32_16x16x32_bf16 v[78:81], v[160:163], v[240:243], v[78:81]
	v_mfma_f32_16x16x32_bf16 v[74:77], v[168:171], v[240:243], v[74:77]
	s_setprio 0
	s_setprio 1
	v_mfma_f32_16x16x32_bf16 v[118:121], v[172:175], v[212:215], v[118:121]
	v_mfma_f32_16x16x32_bf16 v[114:117], v[180:183], v[212:215], v[114:117]
	v_mfma_f32_16x16x32_bf16 v[102:105], v[172:175], v[220:223], v[102:105]
	v_mfma_f32_16x16x32_bf16 v[98:101], v[180:183], v[220:223], v[98:101]
	v_mfma_f32_16x16x32_bf16 v[86:89], v[172:175], v[228:231], v[86:89]
	v_mfma_f32_16x16x32_bf16 v[82:85], v[180:183], v[228:231], v[82:85]
	v_mfma_f32_16x16x32_bf16 v[70:73], v[172:175], v[236:239], v[70:73]
	v_mfma_f32_16x16x32_bf16 v[66:69], v[180:183], v[236:239], v[66:69]
	v_mfma_f32_16x16x32_bf16 v[118:121], v[176:179], v[216:219], v[118:121]
	v_mfma_f32_16x16x32_bf16 v[114:117], v[208:211], v[216:219], v[114:117]
	v_mfma_f32_16x16x32_bf16 v[102:105], v[176:179], v[224:227], v[102:105]
	v_mfma_f32_16x16x32_bf16 v[98:101], v[208:211], v[224:227], v[98:101]
	v_mfma_f32_16x16x32_bf16 v[86:89], v[176:179], v[232:235], v[86:89]
	v_mfma_f32_16x16x32_bf16 v[82:85], v[208:211], v[232:235], v[82:85]
	v_mfma_f32_16x16x32_bf16 v[70:73], v[176:179], v[240:243], v[70:73]
	v_mfma_f32_16x16x32_bf16 v[66:69], v[208:211], v[240:243], v[66:69]
	s_setprio 0
	s_barrier
	s_add_i32 s71, s71, s80
	v_lshl_add_u64 v[202:203], s[34:35], 0, v[132:133]
	s_mov_b32 m0, s71
	ds_read_b128 v[212:215], v154 offset:16384
	ds_read_b128 v[216:219], v154 offset:17408
	ds_read_b128 v[220:223], v154 offset:18432
	ds_read_b128 v[224:227], v154 offset:19456
	ds_read_b128 v[228:231], v154 offset:20480
	ds_read_b128 v[232:235], v154 offset:21504
	ds_read_b128 v[236:239], v154 offset:22528
	ds_read_b128 v[240:243], v154 offset:23552
	global_load_lds_dwordx4 v[202:203], off
	s_add_i32 m0, s71, 0x2000
	s_add_u32 s72, s34, 0x40000
	v_lshl_add_u64 v[204:205], s[34:35], 0, v[130:131]
	s_addc_u32 s73, s35, 0
	s_add_i32 s71, s74, s80
	global_load_lds_dwordx4 v[204:205], off
	v_lshl_add_u64 v[244:245], s[72:73], 0, v[132:133]
	s_mov_b32 m0, s71
	v_lshl_add_u64 v[246:247], s[40:41], 0, v[130:131]
	global_load_lds_dwordx4 v[244:245], off
	v_lshl_add_u64 v[244:245], s[72:73], 0, v[130:131]
	s_add_i32 m0, s71, 0x2000
	s_nop 0
	global_load_lds_dwordx4 v[244:245], off
	v_lshl_add_u64 v[244:245], s[40:41], 0, v[132:133]
	s_mov_b32 m0, s29
	s_nop 0
	global_load_lds_dwordx4 v[244:245], off
	s_mov_b32 m0, s81
	s_nop 0
	global_load_lds_dwordx4 v[246:247], off
	s_waitcnt vmcnt(8)
	s_waitcnt lgkmcnt(0)
	s_barrier
; #define PG8_STAGE(bufoff, gbase, voff) do { _Pragma("unroll") for (int _i = 0; _i < 2; ++_i) \
;         __builtin_amdgcn_global_load_lds((const unsigned*)((const char*)(gbase) + (voff)[_i]), (PG8_LAS unsigned*)(lds + (bufoff) + ldsw + _i * 8192), 16, 0, 0); } while (0)
; #define PG8_LDA(dst, b, h) do { _Pragma("unroll") for (int m = 0; m < 4; ++m) _Pragma("unroll") for (int k = 0; k < 2; ++k) dst[m][k] = *(const PG8_LAS bf16x8*)(lds + PG8_SA(b, h) + aoff + m * 2048 + k * 1024); } while (0)
; #define PG8_LDB(dst, b, h) do { _Pragma("unroll") for (int n = 0; n < 2; ++n) _Pragma("unroll") for (int k = 0; k < 2; ++k) dst[n][k] = *(const PG8_LAS bf16x8*)(lds + PG8_SB(b, h) + boff + n * 2048 + k * 1024); } while (0)
; #define PG8_MMA(ai, bj, At, Bt) do { __builtin_amdgcn_s_setprio(1); _Pragma("unroll") for (int m = 0; m < 4; ++m) _Pragma("unroll") for (int n = 0; n < 2; ++n) _Pragma("unroll") for (int k = 0; k < 2; ++k) \
;         acc[ai][bj][m][n] = __builtin_amdgcn_mfma_f32_16x16x32_bf16(Bt[n][k], At[m][k], acc[ai][bj][m][n], 0, 0, 0); __builtin_amdgcn_s_setprio(0); } while (0)
; #define PG8_WAIT_V(n) asm volatile("s_waitcnt vmcnt(" #n ")" ::: "memory")
; #define PG8_WAIT_L(n) asm volatile("s_waitcnt lgkmcnt(" #n ")" ::: "memory")
; #define PG8_BAR __builtin_amdgcn_s_barrier()
; #define PG8_SCHED __builtin_amdgcn_sched_barrier(0)
; template <class Epi, class Sched, bool ALIGN_EPI = false, bool SP2 = false>
; __device__ __forceinline__ void gemm_phase(PG8_LAS unsigned char* lds, const Gemm g, const Sched& S, const Epi& E) {
;     ...
;             PG8_WAIT_V(8); PG8_WAIT_L(0); PG8_BAR; PG8_MMA(1, 0, At, B0); PG8_MMA(1, 1, At, B1); PG8_BAR; PG8_SCHED;
;             PG8_LDB(B0, 1, 0); PG8_LDB(B1, 1, 1); PG8_SCHED; PG8_LDA(At, 1, 0); PG8_STAGE(PG8_SA(0, 1), a2 + hstep, voffA);
;             PG8_WAIT_V(8); PG8_WAIT_L(0); PG8_BAR; PG8_MMA(0, 0, At, B0); PG8_MMA(0, 1, At, B1); PG8_BAR; PG8_SCHED;
	s_setprio 1
	s_waitcnt lgkmcnt(0)
	v_mfma_f32_16x16x32_bf16 v[62:65], v[156:159], v[212:215], v[62:65]
	v_mfma_f32_16x16x32_bf16 v[58:61], v[164:167], v[212:215], v[58:61]
	v_mfma_f32_16x16x32_bf16 v[46:49], v[156:159], v[220:223], v[46:49]
	v_mfma_f32_16x16x32_bf16 v[42:45], v[164:167], v[220:223], v[42:45]
	v_mfma_f32_16x16x32_bf16 v[30:33], v[156:159], v[228:231], v[30:33]
	v_mfma_f32_16x16x32_bf16 v[26:29], v[164:167], v[228:231], v[26:29]
	v_mfma_f32_16x16x32_bf16 v[14:17], v[156:159], v[236:239], v[14:17]
	v_mfma_f32_16x16x32_bf16 v[10:13], v[164:167], v[236:239], v[10:13]
	v_mfma_f32_16x16x32_bf16 v[62:65], v[160:163], v[216:219], v[62:65]
	v_mfma_f32_16x16x32_bf16 v[58:61], v[168:171], v[216:219], v[58:61]
	v_mfma_f32_16x16x32_bf16 v[46:49], v[160:163], v[224:227], v[46:49]
	v_mfma_f32_16x16x32_bf16 v[42:45], v[168:171], v[224:227], v[42:45]
	v_mfma_f32_16x16x32_bf16 v[30:33], v[160:163], v[232:235], v[30:33]
	v_mfma_f32_16x16x32_bf16 v[26:29], v[168:171], v[232:235], v[26:29]
	v_mfma_f32_16x16x32_bf16 v[14:17], v[160:163], v[240:243], v[14:17]
	v_mfma_f32_16x16x32_bf16 v[10:13], v[168:171], v[240:243], v[10:13]
	s_setprio 0
	s_setprio 1
	v_mfma_f32_16x16x32_bf16 v[54:57], v[172:175], v[212:215], v[54:57]
	v_mfma_f32_16x16x32_bf16 v[50:53], v[180:183], v[212:215], v[50:53]
	v_mfma_f32_16x16x32_bf16 v[38:41], v[172:175], v[220:223], v[38:41]
	v_mfma_f32_16x16x32_bf16 v[34:37], v[180:183], v[220:223], v[34:37]
	v_mfma_f32_16x16x32_bf16 v[22:25], v[172:175], v[228:231], v[22:25]
	v_mfma_f32_16x16x32_bf16 v[18:21], v[180:183], v[228:231], v[18:21]
	v_mfma_f32_16x16x32_bf16 v[6:9], v[172:175], v[236:239], v[6:9]
	v_mfma_f32_16x16x32_bf16 v[2:5], v[180:183], v[236:239], v[2:5]
	v_mfma_f32_16x16x32_bf16 v[54:57], v[176:179], v[216:219], v[54:57]
	v_mfma_f32_16x16x32_bf16 v[50:53], v[208:211], v[216:219], v[50:53]
	v_mfma_f32_16x16x32_bf16 v[38:41], v[176:179], v[224:227], v[38:41]
	v_mfma_f32_16x16x32_bf16 v[34:37], v[208:211], v[224:227], v[34:37]
	v_mfma_f32_16x16x32_bf16 v[22:25], v[176:179], v[232:235], v[22:25]
	v_mfma_f32_16x16x32_bf16 v[18:21], v[208:211], v[232:235], v[18:21]
	v_mfma_f32_16x16x32_bf16 v[6:9], v[176:179], v[240:243], v[6:9]
	v_mfma_f32_16x16x32_bf16 v[2:5], v[208:211], v[240:243], v[2:5]
	s_setprio 0
	s_barrier
	s_add_i32 s71, 0, 0x18000
	v_add_u32_e32 v155, s71, v145
	s_add_i32 s72, 0, 0x1c000
	ds_read_b128 v[156:159], v155
	ds_read_b128 v[160:163], v155 offset:1024
	ds_read_b128 v[164:167], v155 offset:2048
	ds_read_b128 v[168:171], v155 offset:3072
	v_add_u32_e32 v155, s72, v145
	ds_read_b128 v[172:175], v155
	ds_read_b128 v[176:179], v155 offset:1024
	ds_read_b128 v[180:183], v155 offset:2048
	ds_read_b128 v[208:211], v155 offset:3072
	s_add_u32 s40, s40, 0x40000
	s_addc_u32 s41, s41, 0
	s_mov_b32 m0, s82
	v_lshl_add_u64 v[248:249], s[40:41], 0, v[132:133]
	ds_read_b128 v[212:215], v154 offset:32768
	ds_read_b128 v[216:219], v154 offset:33792
	ds_read_b128 v[220:223], v154 offset:34816
	ds_read_b128 v[224:227], v154 offset:35840
	ds_read_b128 v[228:231], v154 offset:36864
	ds_read_b128 v[232:235], v154 offset:37888
	ds_read_b128 v[236:239], v154 offset:38912
	ds_read_b128 v[240:243], v154 offset:39936
	global_load_lds_dwordx4 v[248:249], off
	v_lshl_add_u64 v[248:249], s[40:41], 0, v[130:131]
	s_mov_b32 m0, s83
	s_nop 0
	global_load_lds_dwordx4 v[248:249], off
	s_waitcnt vmcnt(8)
	s_waitcnt lgkmcnt(0)
	s_barrier
	s_setprio 1
	s_waitcnt lgkmcnt(0)
	v_mfma_f32_16x16x32_bf16 v[126:129], v[156:159], v[212:215], v[126:129]
	v_mfma_f32_16x16x32_bf16 v[122:125], v[164:167], v[212:215], v[122:125]
	v_mfma_f32_16x16x32_bf16 v[110:113], v[156:159], v[220:223], v[110:113]
	v_mfma_f32_16x16x32_bf16 v[106:109], v[164:167], v[220:223], v[106:109]
	v_mfma_f32_16x16x32_bf16 v[94:97], v[156:159], v[228:231], v[94:97]
	v_mfma_f32_16x16x32_bf16 v[90:93], v[164:167], v[228:231], v[90:93]
	v_mfma_f32_16x16x32_bf16 v[78:81], v[156:159], v[236:239], v[78:81]
	v_mfma_f32_16x16x32_bf16 v[74:77], v[164:167], v[236:239], v[74:77]
	v_mfma_f32_16x16x32_bf16 v[126:129], v[160:163], v[216:219], v[126:129]
	v_mfma_f32_16x16x32_bf16 v[122:125], v[168:171], v[216:219], v[122:125]
	v_mfma_f32_16x16x32_bf16 v[110:113], v[160:163], v[224:227], v[110:113]
	v_mfma_f32_16x16x32_bf16 v[106:109], v[168:171], v[224:227], v[106:109]
	v_mfma_f32_16x16x32_bf16 v[94:97], v[160:163], v[232:235], v[94:97]
	v_mfma_f32_16x16x32_bf16 v[90:93], v[168:171], v[232:235], v[90:93]
	v_mfma_f32_16x16x32_bf16 v[78:81], v[160:163], v[240:243], v[78:81]
	v_mfma_f32_16x16x32_bf16 v[74:77], v[168:171], v[240:243], v[74:77]
	s_setprio 0
	s_setprio 1
	v_mfma_f32_16x16x32_bf16 v[118:121], v[172:175], v[212:215], v[118:121]
	v_mfma_f32_16x16x32_bf16 v[114:117], v[180:183], v[212:215], v[114:117]
	v_mfma_f32_16x16x32_bf16 v[102:105], v[172:175], v[220:223], v[102:105]
	v_mfma_f32_16x16x32_bf16 v[98:101], v[180:183], v[220:223], v[98:101]
	v_mfma_f32_16x16x32_bf16 v[86:89], v[172:175], v[228:231], v[86:89]
	v_mfma_f32_16x16x32_bf16 v[82:85], v[180:183], v[228:231], v[82:85]
	v_mfma_f32_16x16x32_bf16 v[70:73], v[172:175], v[236:239], v[70:73]
	v_mfma_f32_16x16x32_bf16 v[66:69], v[180:183], v[236:239], v[66:69]
	v_mfma_f32_16x16x32_bf16 v[118:121], v[176:179], v[216:219], v[118:121]
	v_mfma_f32_16x16x32_bf16 v[114:117], v[208:211], v[216:219], v[114:117]
	v_mfma_f32_16x16x32_bf16 v[102:105], v[176:179], v[224:227], v[102:105]
	v_mfma_f32_16x16x32_bf16 v[98:101], v[208:211], v[224:227], v[98:101]
	v_mfma_f32_16x16x32_bf16 v[86:89], v[176:179], v[232:235], v[86:89]
	v_mfma_f32_16x16x32_bf16 v[82:85], v[208:211], v[232:235], v[82:85]
	v_mfma_f32_16x16x32_bf16 v[70:73], v[176:179], v[240:243], v[70:73]
	v_mfma_f32_16x16x32_bf16 v[66:69], v[208:211], v[240:243], v[66:69]
	s_setprio 0
	s_barrier
; #define PG8_STAGE(bufoff, gbase, voff) do { _Pragma("unroll") for (int _i = 0; _i < 2; ++_i) \
;         __builtin_amdgcn_global_load_lds((const unsigned*)((const char*)(gbase) + (voff)[_i]), (PG8_LAS unsigned*)(lds + (bufoff) + ldsw + _i * 8192), 16, 0, 0); } while (0)
; #define PG8_LDA(dst, b, h) do { _Pragma("unroll") for (int m = 0; m < 4; ++m) _Pragma("unroll") for (int k = 0; k < 2; ++k) dst[m][k] = *(const PG8_LAS bf16x8*)(lds + PG8_SA(b, h) + aoff + m * 2048 + k * 1024); } while (0)
; #define PG8_MMA(ai, bj, At, Bt) do { __builtin_amdgcn_s_setprio(1); _Pragma("unroll") for (int m = 0; m < 4; ++m) _Pragma("unroll") for (int n = 0; n < 2; ++n) _Pragma("unroll") for (int k = 0; k < 2; ++k) \
;         acc[ai][bj][m][n] = __builtin_amdgcn_mfma_f32_16x16x32_bf16(Bt[n][k], At[m][k], acc[ai][bj][m][n], 0, 0, 0); __builtin_amdgcn_s_setprio(0); } while (0)
; #define PG8_WAIT_V(n) asm volatile("s_waitcnt vmcnt(" #n ")" ::: "memory")
; #define PG8_WAIT_L(n) asm volatile("s_waitcnt lgkmcnt(" #n ")" ::: "memory")
; #define PG8_BAR __builtin_amdgcn_s_barrier()
; #define PG8_SCHED __builtin_amdgcn_sched_barrier(0)
; template <class Epi, class Sched, bool ALIGN_EPI = false, bool SP2 = false>
; __device__ __forceinline__ void gemm_phase(PG8_LAS unsigned char* lds, const Gemm g, const Sched& S, const Epi& E) {
;     ...
;         for (int t = 0; t < nt; t += 2) {
;             const bool last = (t == nt - 2);
;             const char* a1 = cA + (size_t)(t + 1) * kstep;
;             const char* a2 = last ? nA : cA + (size_t)(t + 2) * kstep; const char* b2 = last ? nB : cB + (size_t)(t + 2) * kstep;
;     ...
;             PG8_LDA(At, 1, 1); PG8_STAGE(PG8_SB(1, 0), b3, voffB); PG8_STAGE(PG8_SB(1, 1), b3 + hstep, voffB); PG8_STAGE(PG8_SA(1, 0), a3, voffA);
;             PG8_WAIT_V(8); PG8_WAIT_L(0); PG8_BAR; PG8_MMA(1, 0, At, B0); PG8_MMA(1, 1, At, B1); PG8_BAR; PG8_SCHED;
	s_add_i32 s40, s71, s80
	v_lshl_add_u64 v[202:203], v[202:203], 0, s[66:67]
	s_mov_b32 m0, s40
	ds_read_b128 v[212:215], v154 offset:49152
	ds_read_b128 v[216:219], v154 offset:50176
	ds_read_b128 v[220:223], v154 offset:51200
	ds_read_b128 v[224:227], v154 offset:52224
	ds_read_b128 v[228:231], v154 offset:53248
	ds_read_b128 v[232:235], v154 offset:54272
	ds_read_b128 v[236:239], v154 offset:55296
	ds_read_b128 v[240:243], v154 offset:56320
	global_load_lds_dwordx4 v[202:203], off
	s_add_i32 m0, s40, 0x2000
	s_add_u32 s34, s34, 0x40080
	v_lshl_add_u64 v[202:203], v[204:205], 0, s[66:67]
	s_addc_u32 s35, s35, 0
	s_add_i32 s40, s72, s80
	global_load_lds_dwordx4 v[202:203], off
	v_lshl_add_u64 v[202:203], s[34:35], 0, v[132:133]
	s_mov_b32 m0, s40
	s_nop 0
	global_load_lds_dwordx4 v[202:203], off
	v_lshl_add_u64 v[202:203], s[34:35], 0, v[130:131]
	s_add_i32 m0, s40, 0x2000
	s_nop 0
	global_load_lds_dwordx4 v[202:203], off
	v_lshl_add_u64 v[202:203], v[244:245], 0, s[66:67]
	s_mov_b32 m0, s84
	s_nop 0
	global_load_lds_dwordx4 v[202:203], off
	v_lshl_add_u64 v[202:203], v[246:247], 0, s[66:67]
	s_mov_b32 m0, s85
	s_nop 0
	global_load_lds_dwordx4 v[202:203], off
	s_waitcnt vmcnt(8)
	s_waitcnt lgkmcnt(0)
	s_barrier
	s_setprio 1
	s_waitcnt lgkmcnt(0)
	v_mfma_f32_16x16x32_bf16 v[62:65], v[156:159], v[212:215], v[62:65]
	v_mfma_f32_16x16x32_bf16 v[58:61], v[164:167], v[212:215], v[58:61]
	v_mfma_f32_16x16x32_bf16 v[46:49], v[156:159], v[220:223], v[46:49]
	v_mfma_f32_16x16x32_bf16 v[42:45], v[164:167], v[220:223], v[42:45]
	v_mfma_f32_16x16x32_bf16 v[30:33], v[156:159], v[228:231], v[30:33]
	v_mfma_f32_16x16x32_bf16 v[26:29], v[164:167], v[228:231], v[26:29]
	v_mfma_f32_16x16x32_bf16 v[14:17], v[156:159], v[236:239], v[14:17]
	v_mfma_f32_16x16x32_bf16 v[10:13], v[164:167], v[236:239], v[10:13]
	v_mfma_f32_16x16x32_bf16 v[62:65], v[160:163], v[216:219], v[62:65]
	v_mfma_f32_16x16x32_bf16 v[58:61], v[168:171], v[216:219], v[58:61]
	v_mfma_f32_16x16x32_bf16 v[46:49], v[160:163], v[224:227], v[46:49]
	v_mfma_f32_16x16x32_bf16 v[42:45], v[168:171], v[224:227], v[42:45]
	v_mfma_f32_16x16x32_bf16 v[30:33], v[160:163], v[232:235], v[30:33]
	v_mfma_f32_16x16x32_bf16 v[26:29], v[168:171], v[232:235], v[26:29]
	v_mfma_f32_16x16x32_bf16 v[14:17], v[160:163], v[240:243], v[14:17]
	v_mfma_f32_16x16x32_bf16 v[10:13], v[168:171], v[240:243], v[10:13]
	s_setprio 0
	s_setprio 1
	v_mfma_f32_16x16x32_bf16 v[54:57], v[172:175], v[212:215], v[54:57]
	v_mfma_f32_16x16x32_bf16 v[50:53], v[180:183], v[212:215], v[50:53]
	v_mfma_f32_16x16x32_bf16 v[38:41], v[172:175], v[220:223], v[38:41]
	v_mfma_f32_16x16x32_bf16 v[34:37], v[180:183], v[220:223], v[34:37]
	v_mfma_f32_16x16x32_bf16 v[22:25], v[172:175], v[228:231], v[22:25]
	v_mfma_f32_16x16x32_bf16 v[18:21], v[180:183], v[228:231], v[18:21]
	v_mfma_f32_16x16x32_bf16 v[6:9], v[172:175], v[236:239], v[6:9]
	v_mfma_f32_16x16x32_bf16 v[2:5], v[180:183], v[236:239], v[2:5]
	v_mfma_f32_16x16x32_bf16 v[54:57], v[176:179], v[216:219], v[54:57]
	v_mfma_f32_16x16x32_bf16 v[50:53], v[208:211], v[216:219], v[50:53]
	v_mfma_f32_16x16x32_bf16 v[38:41], v[176:179], v[224:227], v[38:41]
	v_mfma_f32_16x16x32_bf16 v[34:37], v[208:211], v[224:227], v[34:37]
	v_mfma_f32_16x16x32_bf16 v[22:25], v[176:179], v[232:235], v[22:25]
	v_mfma_f32_16x16x32_bf16 v[18:21], v[208:211], v[232:235], v[18:21]
	v_mfma_f32_16x16x32_bf16 v[6:9], v[176:179], v[240:243], v[6:9]
	v_mfma_f32_16x16x32_bf16 v[2:5], v[208:211], v[240:243], v[2:5]
	s_setprio 0
	s_barrier
	s_add_i32 s62, s62, 2
	s_add_u32 s30, s30, 0x100
	s_addc_u32 s31, s31, 0
	s_add_u32 s52, s52, 0x100
	s_addc_u32 s54, s54, 0
	s_cmp_gt_u32 s62, 13
	s_cbranch_scc0 .LBB0_163
	s_branch .Lku_exit
	s_nop 0
	s_nop 0

; __device__ __forceinline__ void na_task(const P& p, int task, int lane, float* ldsw  ) {
;     const int fr = lane & 15, g = lane >> 4;
;     const bf16_t* QK = (const bf16_t*)(p.ws + WS_NAQK); const bf16_t* VT = (const bf16_t*)(p.ws + WS_NAVT); bf16_t* Y = (bf16_t*)(p.ws + WS_A);
;     if (task < 2048) {
;         const int h = task & 7, r = (task >> 3) & 31, b = task >> 8;
;         for (int i = lane; i < 465; i += 64) ldsw[i] = p.rpb[h * 465 + i];
;         AttnState st[4];
;         bf16_t* qlds = (bf16_t*)(ldsw + 512) + fr * 72 + g * 8;
;         const size_t qrow0 = (size_t)b * TLAT + r * 64 + fr;
; #pragma unroll
;         for (int j = 0; j < 4; ++j) {
;             st[j].m = -1e30f; st[j].l = 0.f;
; #pragma unroll
;             for (int dt = 0; dt < 4; ++dt) st[j].o[dt] = (f32x4){0.f, 0.f, 0.f, 0.f};
;             const bf16_t* qp = QK + (qrow0 + j * 16) * 1024 + h * 64 + g * 8;
;             *(bf16x8*)(qlds + j * 16 * 72) = *(const bf16x8*)qp; *(bf16x8*)(qlds + j * 16 * 72 + 32) = *(const bf16x8*)(qp + 32);
;         }
;         const int r0 = clampi(r - 4, 0, 24);
;         const bf16_t* vb = VT + ((size_t)b * 512 + h * 64) * TT;
;         const bf16_t* kbase = QK + 512 + h * 64 + g * 8;
;     ...
;                 if (i < 16) {
;                     const int qcol = j * 16 + fr, cst = clampi(qcol - 8, 0, 48);
; #pragma unroll
;                     for (int q8 = 0; q8 < 8; ++q8) { const int kk = (q8 < 4) ? 4 * g + q8 : 12 + 4 * g + q8; const int kcc = half * 32 + kk;
;                         const bool ok = (kcc >= cst) && (kcc < cst + 16); const float bv = rp[clampi(kcc - qcol + 15, 0, 30)]; mbv[q8] = ok ? bv : -2e30f; }
.Lst_na:
	v_readlane_b32 s2, v254, 18
	v_readfirstlane_b32 s49, v144
	s_ashr_i32 s48, s49, 6
	s_add_i32 s84, s2, s48
	s_cmpk_gt_i32 s84, 0xbff
	v_readfirstlane_b32 s2, v0
	s_cbranch_scc1 .LBB0_418
	s_load_dwordx2 s[44:45], s[92:93], s2 offset:0x58
	s_load_dwordx2 s[46:47], s[92:93], s2 offset:0xa8
	s_mul_i32 s2, s48, 0x3000
	v_and_b32_e32 v2, 48, v144
	v_mov_b32_e32 v3, v1
	s_add_i32 s85, s2, 0
	v_and_b32_e32 v114, 15, v144
	s_waitcnt lgkmcnt(0)
	v_lshl_add_u64 v[4:5], s[46:47], 0, v[2:3]
	s_mov_b64 s[6:7], 0x7f00400
	s_add_u32 s2, s46, 0x7f00000
	v_lshl_add_u64 v[116:117], v[4:5], 0, s[6:7]
	v_mul_u32_u24_e32 v4, 0x90, v114
	v_bfe_u32 v6, v144, 4, 2
	s_addc_u32 s3, s47, 0
	v_add3_u32 v143, s85, v4, v2
	v_subrev_co_u32_e32 v4, vcc, 8, v114
	s_add_u32 s86, s46, 0xa300000
	v_min_u32_e32 v4, 48, v4
	v_lshlrev_b32_e32 v124, 2, v6
	s_addc_u32 s87, s47, 0
	v_cndmask_b32_e64 v8, v4, 0, vcc
	v_or_b32_e32 v170, 16, v124
	s_add_u32 s76, s46, 0x5b00000
	v_add_u32_e32 v9, 16, v8
	v_cmp_lt_u32_e64 s[8:9], v124, v8
	v_cmp_ge_u32_e32 vcc, v170, v8
	v_or_b32_e32 v172, 17, v124
	s_addc_u32 s77, s47, 0
	s_and_b64 s[14:15], vcc, s[8:9]
	v_cmp_ge_u32_e32 vcc, v172, v8
	v_cmp_lt_u32_e64 s[16:17], v172, v9
	v_or_b32_e32 v174, 18, v124
	v_and_b32_e32 v7, 63, v144
	v_or_b32_e32 v167, 1, v124
	v_or_b32_e32 v168, 3, v124
	v_or_b32_e32 v169, 2, v124
	v_sub_u32_e32 v10, v170, v114
	s_and_b64 s[16:17], vcc, s[16:17]
	v_cmp_ge_u32_e32 vcc, v174, v8
	v_cmp_lt_u32_e64 s[18:19], v174, v9
	v_or_b32_e32 v176, 19, v124
	v_or_b32_e32 v5, 48, v7
	v_cmp_lt_u32_e64 s[6:7], v167, v8
	v_cmp_lt_u32_e64 s[10:11], v168, v8
	v_cmp_lt_u32_e64 s[12:13], v169, v8
	v_min_u32_e32 v171, 15, v10
	v_sub_u32_e32 v10, v172, v114
	s_and_b64 s[18:19], vcc, s[18:19]
	v_cmp_ge_u32_e32 vcc, v176, v8
	v_sub_u32_e32 v8, v176, v114
	v_min_u32_e32 v173, 15, v10
	v_sub_u32_e32 v10, v174, v114
	v_min_u32_e32 v177, 15, v8
	v_add_u32_e32 v8, -8, v5
	v_min_u32_e32 v175, 15, v10
	v_min_u32_e32 v8, 48, v8
	v_or_b32_e32 v10, 32, v124
	v_cmp_lt_u32_e64 s[22:23], v10, v8
	v_sub_u32_e32 v10, v10, v5
	v_sub_u32_e64 v183, v10, -15 clamp
	v_or_b32_e32 v10, 33, v124
	v_cmp_lt_u32_e64 s[24:25], v10, v8
	v_sub_u32_e32 v10, v10, v5
	v_sub_u32_e64 v207, v10, -15 clamp
	v_or_b32_e32 v10, 34, v124
	v_cmp_lt_u32_e64 s[26:27], v10, v8
	v_sub_u32_e32 v10, v10, v5
	s_bfe_u32 s49, s49, 0x30006
	v_sub_u32_e64 v208, v10, -15 clamp
	v_or_b32_e32 v10, 35, v124
	v_lshl_add_u64 v[2:3], s[2:3], 0, v[2:3]
	s_lshl_b32 s64, s49, 7
	v_cmp_lt_u32_e64 s[20:21], v176, v9
	v_add_u32_e32 v9, 16, v8
	v_cmp_lt_u32_e64 s[28:29], v10, v8
	v_sub_u32_e32 v8, v10, v5
	v_lshl_add_u64 v[126:127], v[2:3], 0, s[64:65]
	v_lshrrev_b32_e32 v2, 1, v144
	v_sub_u32_e64 v209, v8, -15 clamp
	v_or_b32_e32 v8, 49, v124
	v_or_b32_e32 v10, 48, v124
	v_and_b32_e32 v2, 24, v2
	v_mov_b32_e32 v3, v1
	v_lshlrev_b32_e32 v0, 3, v6
	v_sub_u32_e32 v210, v10, v5
	v_cmp_lt_u32_e64 s[30:31], v8, v9
	v_cmp_lt_u32_e64 s[34:35], v10, v9
	v_or_b32_e32 v8, 51, v124
	v_or_b32_e32 v10, 50, v124
	s_mul_i32 s50, s49, 0x1d1
	v_lshl_add_u64 v[132:133], s[46:47], 0, v[2:3]
	v_readlane_b32 s46, v254, 19
	v_mul_u32_u24_e32 v118, 0x1200, v114
	v_or_b32_e32 v4, 0x800, v124
	v_or_b32_e32 v6, 0x810, v124
	v_cmp_lt_u32_e64 s[40:41], v8, v9
	v_cmp_lt_u32_e64 s[42:43], v10, v9
	v_lshl_add_u64 v[8:9], s[76:77], 0, v[0:1]
	s_add_i32 s89, s46, s48
	s_lshl_b32 s46, s48, 6
	v_readlane_b32 s47, v254, 21
	v_add_lshl_u32 v2, s50, v7, 2
	v_mov_b32_e32 v119, v1
	v_mul_u32_u24_e32 v120, 0x1200, v5
	v_mov_b32_e32 v121, v1
	v_or_b32_e32 v125, 0x4000, v114
	v_mov_b32_e32 v115, v1
	v_mul_hi_u32_u24_e32 v123, 0x1200, v114
	v_mov_b32_e32 v122, v118
	v_bitop3_b32 v145, v144, 15, v144 bitop3:0xc
	s_and_b64 s[20:21], vcc, s[20:21]
	v_or_b32_e32 v178, 16, v114
	v_add_u32_e32 v179, 8, v114
	v_add_u32_e32 v180, 24, v114
	v_or_b32_e32 v181, 32, v114
	v_add_u32_e32 v182, 40, v114
	v_sub_u32_e32 v211, v10, v5
	s_lshl_b32 s88, s49, 6
	v_lshl_add_u64 v[128:129], v[116:117], 0, s[64:65]
	v_lshl_add_u64 v[130:131], v[8:9], 0, s[64:65]
	s_add_i32 s90, s47, s46
	v_lshl_add_u32 v212, v7, 2, s85
	v_or_b32_e32 v213, 0xffffffc0, v7
	v_lshl_add_u64 v[134:135], s[44:45], 0, v[2:3]
	v_lshlrev_b32_e32 v136, 1, v0
	v_lshlrev_b32_e32 v146, 1, v4
	v_lshlrev_b32_e32 v148, 1, v6
	s_branch .LBB0_382
	s_nop 0
	s_nop 0
	s_nop 0
	s_nop 0
	s_nop 0
	s_nop 0
	s_nop 0
	s_nop 0
	s_nop 0

; __device__ __forceinline__ unsigned pk2(float lo, float hi) { unsigned r; asm("v_cvt_pk_bf16_f32 %0, %1, %2" : "=v"(r) : "v"(lo), "v"(hi)); return r; }
; __device__ __forceinline__ float siluf(float v) { return v * __builtin_amdgcn_rcpf(1.f + __expf(-v)); }
; __device__ __forceinline__ void dn_conv_token4(const P& p, int m0, int lane) {
;     ...
;     if (m0 < MLAT) { s0 = m0 & ~2047; s1 = s0 + 2048; } else { s0 = MLAT + ((m0 - MLAT) & ~255); s1 = s0 + 256; }
; #pragma unroll 1
;     for (int cgp = 0; cgp < 3; ++cgp) {
;         const int col = cgp * 512 + lane * 8;
;         f32x4 w[5][2];
; #pragma unroll
;         for (int j = 0; j < 5; ++j) { w[j][0] = *(const f32x4*)(p.conv_w + j * 1536 + col); w[j][1] = *(const f32x4*)(p.conv_w + j * 1536 + col + 4); }
;         u32x4 xr[8];
; #pragma unroll
;         for (int r = 0; r < 8; ++r) { const int mm = m0 + r - 2; xr[r] = (mm >= s0 && mm < s1) ? *(const u32x4*)(PRE + (size_t)mm * 1536 + col) : (u32x4){0u, 0u, 0u, 0u}; }
;         bf16_t* dbase = (bf16_t*)(p.ws + (cgp == 0 ? WS_QN : (cgp == 1 ? WS_KN : WS_VV))) + lane * 8;
; #pragma unroll
;         for (int t = 0; t < 4; ++t) {
;             float acc[8];
; #pragma unroll
;             for (int i = 0; i < 8; ++i) acc[i] = 0.f;
; #pragma unroll
;             for (int j = 0; j < 5; ++j) { const u32x4 xv = xr[t + j];
;                 acc[0] += bflo(xv.x) * w[j][0][0]; acc[1] += bfhi(xv.x) * w[j][0][1]; acc[2] += bflo(xv.y) * w[j][0][2]; acc[3] += bfhi(xv.y) * w[j][0][3];
;                 acc[4] += bflo(xv.z) * w[j][1][0]; acc[5] += bfhi(xv.z) * w[j][1][1]; acc[6] += bflo(xv.w) * w[j][1][2]; acc[7] += bfhi(xv.w) * w[j][1][3]; }
;             float ss = 0.f;
; #pragma unroll
;             for (int i = 0; i < 8; ++i) { acc[i] = siluf(acc[i]); ss += acc[i] * acc[i]; }
;             if (cgp < 2) {
;                 ss += __shfl_xor(ss, 1); ss += __shfl_xor(ss, 2); ss += __shfl_xor(ss, 4); ss += __shfl_xor(ss, 8);
;                 const float rn = 1.0f / sqrtf(ss + EPS);
; #pragma unroll
;                 for (int i = 0; i < 8; ++i) acc[i] *= rn;
;             }
;             u32x4 o; o.x = pk2(acc[0], acc[1]); o.y = pk2(acc[2], acc[3]); o.z = pk2(acc[4], acc[5]); o.w = pk2(acc[6], acc[7]);
;             *(u32x4*)(dbase + (size_t)(m0 + t) * 512) = o;
.LBB0_422:
	s_mul_i32 s9, s15, 0xc00
	s_mul_hi_i32 s8, s15, 0xc00
	s_add_u32 s26, s13, s9
	s_addc_u32 s27, s14, s8
	s_mul_i32 s9, s20, 0xc00
	s_mul_hi_i32 s8, s20, 0xc00
	s_add_u32 s28, s13, s9
	s_addc_u32 s29, s14, s8
	s_mul_i32 s9, s21, 0xc00
	s_mul_hi_i32 s8, s21, 0xc00
	s_add_u32 s30, s13, s9
	s_addc_u32 s31, s14, s8
	s_mul_i32 s9, s12, 0xc00
	s_mul_hi_i32 s8, s12, 0xc00
	s_add_u32 s34, s13, s9
	s_addc_u32 s35, s14, s8
	s_and_b32 s8, s16, 0xfffff800
	s_and_b32 s10, s16, 0x7fffff00
	s_add_i32 s9, s8, 0x800
	s_add_i32 s11, s10, 0x100
	s_cmpk_lt_i32 s16, 0x4000
	s_cselect_b32 s50, s9, s11
	s_cselect_b32 s52, s8, s10
	s_add_i32 s10, s16, -2
	s_cmp_ge_i32 s10, s52
	s_cselect_b64 s[8:9], -1, 0
	s_cmp_lt_i32 s10, s50
	s_cselect_b64 s[10:11], -1, 0
	s_and_b64 s[40:41], s[8:9], s[10:11]
	s_add_i32 s10, s16, -1
	s_cmp_ge_i32 s10, s52
	s_cselect_b64 s[8:9], -1, 0
	s_cmp_lt_i32 s10, s50
	s_cselect_b64 s[10:11], -1, 0
	s_and_b64 s[42:43], s[8:9], s[10:11]
	s_cmp_ge_i32 s16, s52
	s_cselect_b64 s[8:9], -1, 0
	s_cmp_lt_i32 s16, s50
	s_cselect_b64 s[10:11], -1, 0
	s_and_b64 s[44:45], s[8:9], s[10:11]
	s_ashr_i32 s17, s16, 31
	s_or_b32 s8, s16, 1
	s_cmp_ge_i32 s8, s52
	s_cselect_b64 s[10:11], -1, 0
	s_cmp_lt_i32 s8, s50
	s_cselect_b64 s[46:47], -1, 0
	s_and_b64 s[46:47], s[10:11], s[46:47]
	s_ashr_i32 s9, s8, 31
	s_or_b32 s10, s16, 2
	s_cmp_ge_i32 s10, s52
	s_cselect_b64 s[48:49], -1, 0
	s_cmp_lt_i32 s10, s50
	s_cselect_b64 s[72:73], -1, 0
	s_and_b64 s[48:49], s[48:49], s[72:73]
	s_ashr_i32 s11, s10, 31
	s_or_b32 s72, s16, 3
	s_cmp_ge_i32 s72, s52
	s_cselect_b64 s[74:75], -1, 0
	s_cmp_lt_i32 s72, s50
	s_cselect_b64 s[76:77], -1, 0
	s_and_b64 s[76:77], s[74:75], s[76:77]
	s_ashr_i32 s73, s72, 31
	s_add_i32 s54, s16, 4
	s_cmp_ge_i32 s54, s52
	s_cselect_b64 s[74:75], -1, 0
	s_cmp_lt_i32 s54, s50
	s_cselect_b64 s[78:79], -1, 0
	s_and_b64 s[80:81], s[74:75], s[78:79]
	s_add_i32 s54, s16, 5
	s_cmp_ge_i32 s54, s52
	s_cselect_b64 s[74:75], -1, 0
	s_cmp_lt_i32 s54, s50
	s_cselect_b64 s[78:79], -1, 0
	s_and_b64 s[82:83], s[74:75], s[78:79]
	s_lshl_b64 s[84:85], s[16:17], 10
	s_lshl_b64 s[86:87], s[8:9], 10
	s_lshl_b64 s[88:89], s[10:11], 10
	s_lshl_b64 s[90:91], s[72:73], 10
	s_mov_b64 s[92:93], 0
	s_mov_b64 s[94:95], s[24:25]
	s_branch .LBB0_424
	s_nop 0
	s_nop 0
	s_nop 0
	s_nop 0
.LBB0_423:
	s_add_u32 s92, s92, 0x800
	s_addc_u32 s93, s93, 0
	s_add_u32 s26, s26, 0x400
	s_addc_u32 s27, s27, 0
	s_add_u32 s28, s28, 0x400
	s_addc_u32 s29, s29, 0
	s_add_u32 s94, s94, 0x400
	s_addc_u32 s95, s95, 0
	s_add_u32 s30, s30, 0x400
	s_addc_u32 s31, s31, 0
	s_add_u32 s34, s34, 0x400
	s_addc_u32 s35, s35, 0
	v_cvt_pk_bf16_f32 v8, v8, v9
	v_cvt_pk_bf16_f32 v9, v2, v3
	v_lshl_add_u64 v[2:3], v[54:55], 0, s[90:91]
	s_cmpk_eq_i32 s92, 0x1800
	v_cvt_pk_bf16_f32 v10, v4, v5
	v_cvt_pk_bf16_f32 v11, v6, v7
	global_store_dwordx4 v[2:3], v[8:11], off
	s_cbranch_scc1 .LBB0_448

; #define PG8_STAGE(bufoff, gbase, voff) do { _Pragma("unroll") for (int _i = 0; _i < 2; ++_i) \
;         __builtin_amdgcn_global_load_lds((const unsigned*)((const char*)(gbase) + (voff)[_i]), (PG8_LAS unsigned*)(lds + (bufoff) + ldsw + _i * 8192), 16, 0, 0); } while (0)
; #define PG8_LDA(dst, b, h) do { _Pragma("unroll") for (int m = 0; m < 4; ++m) _Pragma("unroll") for (int k = 0; k < 2; ++k) dst[m][k] = *(const PG8_LAS bf16x8*)(lds + PG8_SA(b, h) + aoff + m * 2048 + k * 1024); } while (0)
; #define PG8_LDB(dst, b, h) do { _Pragma("unroll") for (int n = 0; n < 2; ++n) _Pragma("unroll") for (int k = 0; k < 2; ++k) dst[n][k] = *(const PG8_LAS bf16x8*)(lds + PG8_SB(b, h) + boff + n * 2048 + k * 1024); } while (0)
; #define PG8_MMA(ai, bj, At, Bt) do { __builtin_amdgcn_s_setprio(1); _Pragma("unroll") for (int m = 0; m < 4; ++m) _Pragma("unroll") for (int n = 0; n < 2; ++n) _Pragma("unroll") for (int k = 0; k < 2; ++k) \
;         acc[ai][bj][m][n] = __builtin_amdgcn_mfma_f32_16x16x32_bf16(Bt[n][k], At[m][k], acc[ai][bj][m][n], 0, 0, 0); __builtin_amdgcn_s_setprio(0); } while (0)
; #define PG8_WAIT_V(n) asm volatile("s_waitcnt vmcnt(" #n ")" ::: "memory")
; #define PG8_WAIT_L(n) asm volatile("s_waitcnt lgkmcnt(" #n ")" ::: "memory")
; #define PG8_BAR __builtin_amdgcn_s_barrier()
; #define PG8_SCHED __builtin_amdgcn_sched_barrier(0)
; template <class Epi, class Sched, bool ALIGN_EPI = false, bool SP2 = false>
; __device__ __forceinline__ void gemm_phase(PG8_LAS unsigned char* lds, const Gemm g, const Sched& S, const Epi& E) {
;     ...
;             PG8_LDB(B0, 0, 0); PG8_LDB(B1, 0, 1); PG8_SCHED; PG8_LDA(At, 0, 0); PG8_STAGE(PG8_SA(1, 1), a1 + hstep, voffA);
;             PG8_WAIT_V(8); PG8_WAIT_L(0); PG8_BAR; PG8_MMA(0, 0, At, B0); PG8_MMA(0, 1, At, B1); PG8_BAR; PG8_SCHED;
;             PG8_LDA(At, 0, 1); PG8_STAGE(PG8_SB(0, 0), b2, voffB); PG8_STAGE(PG8_SB(0, 1), b2 + hstep, voffB); PG8_STAGE(PG8_SA(0, 0), a2, voffA);
.Lpeel_r:
	s_add_i32 s82, s76, 2
	s_add_u32 s83, s48, 0x80
	s_addc_u32 s77, s49, 0
	s_add_i32 s59, 0, 0x10000
	s_cmp_eq_u32 s72, s76
	s_cselect_b32 s77, s9, s77
	s_cselect_b32 s76, s8, s83
	v_add_u32_e32 v136, s59, v147
	s_cselect_b32 vcc_hi, s47, s81
	s_cselect_b32 vcc_lo, s46, s80
	s_add_i32 s83, 0, 0x14000
	ds_read_b128 v[148:151], v136
	ds_read_b128 v[152:155], v136 offset:1024
	ds_read_b128 v[156:159], v136 offset:2048
	ds_read_b128 v[160:163], v136 offset:3072
	v_add_u32_e32 v136, s83, v147
	ds_read_b128 v[166:169], v136
	ds_read_b128 v[170:173], v136 offset:1024
	ds_read_b128 v[174:177], v136 offset:2048
	ds_read_b128 v[178:181], v136 offset:3072
	v_lshl_add_u64 v[136:137], s[48:49], 0, v[132:133]
	s_add_i32 m0, s94, 0xc000
	ds_read_b128 v[202:205], v165
	ds_read_b128 v[208:211], v165 offset:1024
	ds_read_b128 v[212:215], v165 offset:2048
	ds_read_b128 v[216:219], v165 offset:3072
	ds_read_b128 v[220:223], v165 offset:4096
	ds_read_b128 v[224:227], v165 offset:5120
	ds_read_b128 v[228:231], v165 offset:6144
	ds_read_b128 v[232:235], v165 offset:7168
	global_load_lds_dwordx4 v[136:137], off
	v_lshl_add_u64 v[136:137], s[48:49], 0, v[134:135]
	s_add_i32 m0, s94, 0xe000
	s_nop 0
	global_load_lds_dwordx4 v[136:137], off
	s_waitcnt vmcnt(8)
	s_waitcnt lgkmcnt(0)
	s_barrier
	s_setprio 1
	s_waitcnt lgkmcnt(0)
	v_mfma_f32_16x16x32_bf16 v[126:129], v[148:151], v[202:205], 0
	v_mfma_f32_16x16x32_bf16 v[122:125], v[156:159], v[202:205], 0
	v_mfma_f32_16x16x32_bf16 v[110:113], v[148:151], v[212:215], 0
	v_mfma_f32_16x16x32_bf16 v[106:109], v[156:159], v[212:215], 0
	v_mfma_f32_16x16x32_bf16 v[94:97], v[148:151], v[220:223], 0
	v_mfma_f32_16x16x32_bf16 v[90:93], v[156:159], v[220:223], 0
	v_mfma_f32_16x16x32_bf16 v[78:81], v[148:151], v[228:231], 0
	v_mfma_f32_16x16x32_bf16 v[74:77], v[156:159], v[228:231], 0
	v_mfma_f32_16x16x32_bf16 v[126:129], v[152:155], v[208:211], v[126:129]
	v_mfma_f32_16x16x32_bf16 v[122:125], v[160:163], v[208:211], v[122:125]
	v_mfma_f32_16x16x32_bf16 v[110:113], v[152:155], v[216:219], v[110:113]
	v_mfma_f32_16x16x32_bf16 v[106:109], v[160:163], v[216:219], v[106:109]
	v_mfma_f32_16x16x32_bf16 v[94:97], v[152:155], v[224:227], v[94:97]
	v_mfma_f32_16x16x32_bf16 v[90:93], v[160:163], v[224:227], v[90:93]
	v_mfma_f32_16x16x32_bf16 v[78:81], v[152:155], v[232:235], v[78:81]
	v_mfma_f32_16x16x32_bf16 v[74:77], v[160:163], v[232:235], v[74:77]
	s_setprio 0
	s_setprio 1
	v_mfma_f32_16x16x32_bf16 v[118:121], v[166:169], v[202:205], 0
	v_mfma_f32_16x16x32_bf16 v[114:117], v[174:177], v[202:205], 0
	v_mfma_f32_16x16x32_bf16 v[102:105], v[166:169], v[212:215], 0
	v_mfma_f32_16x16x32_bf16 v[98:101], v[174:177], v[212:215], 0
	v_mfma_f32_16x16x32_bf16 v[86:89], v[166:169], v[220:223], 0
	v_mfma_f32_16x16x32_bf16 v[82:85], v[174:177], v[220:223], 0
	v_mfma_f32_16x16x32_bf16 v[70:73], v[166:169], v[228:231], 0
	v_mfma_f32_16x16x32_bf16 v[66:69], v[174:177], v[228:231], 0
	v_mfma_f32_16x16x32_bf16 v[118:121], v[170:173], v[208:211], v[118:121]
	v_mfma_f32_16x16x32_bf16 v[114:117], v[178:181], v[208:211], v[114:117]
	v_mfma_f32_16x16x32_bf16 v[102:105], v[170:173], v[216:219], v[102:105]
	v_mfma_f32_16x16x32_bf16 v[98:101], v[178:181], v[216:219], v[98:101]
	v_mfma_f32_16x16x32_bf16 v[86:89], v[170:173], v[224:227], v[86:89]
	v_mfma_f32_16x16x32_bf16 v[82:85], v[178:181], v[224:227], v[82:85]
	v_mfma_f32_16x16x32_bf16 v[70:73], v[170:173], v[232:235], v[70:73]
	v_mfma_f32_16x16x32_bf16 v[66:69], v[178:181], v[232:235], v[66:69]
	s_setprio 0
	s_barrier
	s_add_i32 s59, s59, s93
	v_lshl_add_u64 v[136:137], vcc, 0, v[0:1]
	s_mov_b32 m0, s59
	ds_read_b128 v[202:205], v165 offset:16384
	ds_read_b128 v[208:211], v165 offset:17408
	ds_read_b128 v[212:215], v165 offset:18432
	ds_read_b128 v[216:219], v165 offset:19456
	ds_read_b128 v[220:223], v165 offset:20480
	ds_read_b128 v[224:227], v165 offset:21504
	ds_read_b128 v[228:231], v165 offset:22528
	ds_read_b128 v[232:235], v165 offset:23552
	global_load_lds_dwordx4 v[136:137], off
	s_add_i32 m0, s59, 0x2000
	v_lshl_add_u64 v[144:145], vcc, 0, v[130:131]
	s_add_u32 vcc_lo, vcc_lo, s10
	s_addc_u32 vcc_hi, vcc_hi, 0
	s_add_i32 s59, s83, s93
	global_load_lds_dwordx4 v[144:145], off
	v_lshl_add_u64 v[182:183], vcc, 0, v[0:1]
	s_mov_b32 m0, s59
	v_lshl_add_u64 v[236:237], vcc, 0, v[130:131]
	global_load_lds_dwordx4 v[182:183], off
	s_add_i32 m0, s59, 0x2000
	v_lshl_add_u64 v[238:239], s[76:77], 0, v[0:1]
	global_load_lds_dwordx4 v[236:237], off
	s_mov_b32 m0, s94
	v_lshl_add_u64 v[240:241], s[76:77], 0, v[130:131]
	global_load_lds_dwordx4 v[238:239], off
	s_mov_b32 m0, s95
	s_nop 0
	global_load_lds_dwordx4 v[240:241], off
	s_waitcnt vmcnt(8)
	s_waitcnt lgkmcnt(0)
	s_barrier
; #define PG8_STAGE(bufoff, gbase, voff) do { _Pragma("unroll") for (int _i = 0; _i < 2; ++_i) \
;         __builtin_amdgcn_global_load_lds((const unsigned*)((const char*)(gbase) + (voff)[_i]), (PG8_LAS unsigned*)(lds + (bufoff) + ldsw + _i * 8192), 16, 0, 0); } while (0)
; #define PG8_LDA(dst, b, h) do { _Pragma("unroll") for (int m = 0; m < 4; ++m) _Pragma("unroll") for (int k = 0; k < 2; ++k) dst[m][k] = *(const PG8_LAS bf16x8*)(lds + PG8_SA(b, h) + aoff + m * 2048 + k * 1024); } while (0)
; #define PG8_LDB(dst, b, h) do { _Pragma("unroll") for (int n = 0; n < 2; ++n) _Pragma("unroll") for (int k = 0; k < 2; ++k) dst[n][k] = *(const PG8_LAS bf16x8*)(lds + PG8_SB(b, h) + boff + n * 2048 + k * 1024); } while (0)
; #define PG8_MMA(ai, bj, At, Bt) do { __builtin_amdgcn_s_setprio(1); _Pragma("unroll") for (int m = 0; m < 4; ++m) _Pragma("unroll") for (int n = 0; n < 2; ++n) _Pragma("unroll") for (int k = 0; k < 2; ++k) \
;         acc[ai][bj][m][n] = __builtin_amdgcn_mfma_f32_16x16x32_bf16(Bt[n][k], At[m][k], acc[ai][bj][m][n], 0, 0, 0); __builtin_amdgcn_s_setprio(0); } while (0)
; #define PG8_WAIT_V(n) asm volatile("s_waitcnt vmcnt(" #n ")" ::: "memory")
; #define PG8_WAIT_L(n) asm volatile("s_waitcnt lgkmcnt(" #n ")" ::: "memory")
; #define PG8_BAR __builtin_amdgcn_s_barrier()
; #define PG8_SCHED __builtin_amdgcn_sched_barrier(0)
; template <class Epi, class Sched, bool ALIGN_EPI = false, bool SP2 = false>
; __device__ __forceinline__ void gemm_phase(PG8_LAS unsigned char* lds, const Gemm g, const Sched& S, const Epi& E) {
;     ...
;             PG8_WAIT_V(8); PG8_WAIT_L(0); PG8_BAR; PG8_MMA(1, 0, At, B0); PG8_MMA(1, 1, At, B1); PG8_BAR; PG8_SCHED;
;             PG8_LDB(B0, 1, 0); PG8_LDB(B1, 1, 1); PG8_SCHED; PG8_LDA(At, 1, 0); PG8_STAGE(PG8_SA(0, 1), a2 + hstep, voffA);
;             PG8_WAIT_V(8); PG8_WAIT_L(0); PG8_BAR; PG8_MMA(0, 0, At, B0); PG8_MMA(0, 1, At, B1); PG8_BAR; PG8_SCHED;
	s_setprio 1
	s_waitcnt lgkmcnt(0)
	v_mfma_f32_16x16x32_bf16 v[62:65], v[148:151], v[202:205], 0
	v_mfma_f32_16x16x32_bf16 v[58:61], v[156:159], v[202:205], 0
	v_mfma_f32_16x16x32_bf16 v[46:49], v[148:151], v[212:215], 0
	v_mfma_f32_16x16x32_bf16 v[42:45], v[156:159], v[212:215], 0
	v_mfma_f32_16x16x32_bf16 v[30:33], v[148:151], v[220:223], 0
	v_mfma_f32_16x16x32_bf16 v[26:29], v[156:159], v[220:223], 0
	v_mfma_f32_16x16x32_bf16 v[14:17], v[148:151], v[228:231], 0
	v_mfma_f32_16x16x32_bf16 v[10:13], v[156:159], v[228:231], 0
	v_mfma_f32_16x16x32_bf16 v[62:65], v[152:155], v[208:211], v[62:65]
	v_mfma_f32_16x16x32_bf16 v[58:61], v[160:163], v[208:211], v[58:61]
	v_mfma_f32_16x16x32_bf16 v[46:49], v[152:155], v[216:219], v[46:49]
	v_mfma_f32_16x16x32_bf16 v[42:45], v[160:163], v[216:219], v[42:45]
	v_mfma_f32_16x16x32_bf16 v[30:33], v[152:155], v[224:227], v[30:33]
	v_mfma_f32_16x16x32_bf16 v[26:29], v[160:163], v[224:227], v[26:29]
	v_mfma_f32_16x16x32_bf16 v[14:17], v[152:155], v[232:235], v[14:17]
	v_mfma_f32_16x16x32_bf16 v[10:13], v[160:163], v[232:235], v[10:13]
	s_setprio 0
	s_setprio 1
	v_mfma_f32_16x16x32_bf16 v[54:57], v[166:169], v[202:205], 0
	v_mfma_f32_16x16x32_bf16 v[50:53], v[174:177], v[202:205], 0
	v_mfma_f32_16x16x32_bf16 v[38:41], v[166:169], v[212:215], 0
	v_mfma_f32_16x16x32_bf16 v[34:37], v[174:177], v[212:215], 0
	v_mfma_f32_16x16x32_bf16 v[22:25], v[166:169], v[220:223], 0
	v_mfma_f32_16x16x32_bf16 v[18:21], v[174:177], v[220:223], 0
	v_mfma_f32_16x16x32_bf16 v[6:9], v[166:169], v[228:231], 0
	v_mfma_f32_16x16x32_bf16 v[2:5], v[174:177], v[228:231], 0
	v_mfma_f32_16x16x32_bf16 v[54:57], v[170:173], v[208:211], v[54:57]
	v_mfma_f32_16x16x32_bf16 v[50:53], v[178:181], v[208:211], v[50:53]
	v_mfma_f32_16x16x32_bf16 v[38:41], v[170:173], v[216:219], v[38:41]
	v_mfma_f32_16x16x32_bf16 v[34:37], v[178:181], v[216:219], v[34:37]
	v_mfma_f32_16x16x32_bf16 v[22:25], v[170:173], v[224:227], v[22:25]
	v_mfma_f32_16x16x32_bf16 v[18:21], v[178:181], v[224:227], v[18:21]
	v_mfma_f32_16x16x32_bf16 v[6:9], v[170:173], v[232:235], v[6:9]
	v_mfma_f32_16x16x32_bf16 v[2:5], v[178:181], v[232:235], v[2:5]
	s_setprio 0
	s_barrier
	s_add_i32 s59, 0, 0x18000
	s_add_i32 s83, 0, 0x1c000
	v_add_u32_e32 v160, s59, v147
	v_add_u32_e32 v178, s83, v147
	ds_read_b128 v[148:151], v160
	ds_read_b128 v[152:155], v160 offset:1024
	ds_read_b128 v[156:159], v160 offset:2048
	ds_read_b128 v[160:163], v160 offset:3072
	ds_read_b128 v[166:169], v178
	ds_read_b128 v[170:173], v178 offset:1024
	ds_read_b128 v[174:177], v178 offset:2048
	ds_read_b128 v[178:181], v178 offset:3072
	s_add_u32 s76, s76, s10
	s_addc_u32 s77, s77, 0
	s_mov_b32 m0, s84
	v_lshl_add_u64 v[242:243], s[76:77], 0, v[0:1]
	ds_read_b128 v[202:205], v165 offset:32768
	ds_read_b128 v[208:211], v165 offset:33792
	ds_read_b128 v[212:215], v165 offset:34816
	ds_read_b128 v[216:219], v165 offset:35840
	ds_read_b128 v[220:223], v165 offset:36864
	ds_read_b128 v[224:227], v165 offset:37888
	ds_read_b128 v[228:231], v165 offset:38912
	ds_read_b128 v[232:235], v165 offset:39936
	global_load_lds_dwordx4 v[242:243], off
	v_lshl_add_u64 v[242:243], s[76:77], 0, v[130:131]
	s_mov_b32 m0, s74
	s_nop 0
	global_load_lds_dwordx4 v[242:243], off
	s_waitcnt vmcnt(8)
	s_waitcnt lgkmcnt(0)
	s_barrier
	s_setprio 1
	s_waitcnt lgkmcnt(0)
	v_mfma_f32_16x16x32_bf16 v[126:129], v[148:151], v[202:205], v[126:129]
	v_mfma_f32_16x16x32_bf16 v[122:125], v[156:159], v[202:205], v[122:125]
	v_mfma_f32_16x16x32_bf16 v[110:113], v[148:151], v[212:215], v[110:113]
	v_mfma_f32_16x16x32_bf16 v[106:109], v[156:159], v[212:215], v[106:109]
	v_mfma_f32_16x16x32_bf16 v[94:97], v[148:151], v[220:223], v[94:97]
	v_mfma_f32_16x16x32_bf16 v[90:93], v[156:159], v[220:223], v[90:93]
	v_mfma_f32_16x16x32_bf16 v[78:81], v[148:151], v[228:231], v[78:81]
	v_mfma_f32_16x16x32_bf16 v[74:77], v[156:159], v[228:231], v[74:77]
	v_mfma_f32_16x16x32_bf16 v[126:129], v[152:155], v[208:211], v[126:129]
	v_mfma_f32_16x16x32_bf16 v[122:125], v[160:163], v[208:211], v[122:125]
	v_mfma_f32_16x16x32_bf16 v[110:113], v[152:155], v[216:219], v[110:113]
	v_mfma_f32_16x16x32_bf16 v[106:109], v[160:163], v[216:219], v[106:109]
	v_mfma_f32_16x16x32_bf16 v[94:97], v[152:155], v[224:227], v[94:97]
	v_mfma_f32_16x16x32_bf16 v[90:93], v[160:163], v[224:227], v[90:93]
	v_mfma_f32_16x16x32_bf16 v[78:81], v[152:155], v[232:235], v[78:81]
	v_mfma_f32_16x16x32_bf16 v[74:77], v[160:163], v[232:235], v[74:77]
	s_setprio 0
	s_setprio 1
	v_mfma_f32_16x16x32_bf16 v[118:121], v[166:169], v[202:205], v[118:121]
	v_mfma_f32_16x16x32_bf16 v[114:117], v[174:177], v[202:205], v[114:117]
	v_mfma_f32_16x16x32_bf16 v[102:105], v[166:169], v[212:215], v[102:105]
	v_mfma_f32_16x16x32_bf16 v[98:101], v[174:177], v[212:215], v[98:101]
	v_mfma_f32_16x16x32_bf16 v[86:89], v[166:169], v[220:223], v[86:89]
	v_mfma_f32_16x16x32_bf16 v[82:85], v[174:177], v[220:223], v[82:85]
	v_mfma_f32_16x16x32_bf16 v[70:73], v[166:169], v[228:231], v[70:73]
	v_mfma_f32_16x16x32_bf16 v[66:69], v[174:177], v[228:231], v[66:69]
	v_mfma_f32_16x16x32_bf16 v[118:121], v[170:173], v[208:211], v[118:121]
	v_mfma_f32_16x16x32_bf16 v[114:117], v[178:181], v[208:211], v[114:117]
	v_mfma_f32_16x16x32_bf16 v[102:105], v[170:173], v[216:219], v[102:105]
	v_mfma_f32_16x16x32_bf16 v[98:101], v[178:181], v[216:219], v[98:101]
	v_mfma_f32_16x16x32_bf16 v[86:89], v[170:173], v[224:227], v[86:89]
	v_mfma_f32_16x16x32_bf16 v[82:85], v[178:181], v[224:227], v[82:85]
	v_mfma_f32_16x16x32_bf16 v[70:73], v[170:173], v[232:235], v[70:73]
	v_mfma_f32_16x16x32_bf16 v[66:69], v[178:181], v[232:235], v[66:69]
	s_setprio 0
	s_barrier
; #define PG8_STAGE(bufoff, gbase, voff) do { _Pragma("unroll") for (int _i = 0; _i < 2; ++_i) \
;         __builtin_amdgcn_global_load_lds((const unsigned*)((const char*)(gbase) + (voff)[_i]), (PG8_LAS unsigned*)(lds + (bufoff) + ldsw + _i * 8192), 16, 0, 0); } while (0)
; #define PG8_LDA(dst, b, h) do { _Pragma("unroll") for (int m = 0; m < 4; ++m) _Pragma("unroll") for (int k = 0; k < 2; ++k) dst[m][k] = *(const PG8_LAS bf16x8*)(lds + PG8_SA(b, h) + aoff + m * 2048 + k * 1024); } while (0)
; #define PG8_LDB(dst, b, h) do { _Pragma("unroll") for (int n = 0; n < 2; ++n) _Pragma("unroll") for (int k = 0; k < 2; ++k) dst[n][k] = *(const PG8_LAS bf16x8*)(lds + PG8_SB(b, h) + boff + n * 2048 + k * 1024); } while (0)
; #define PG8_MMA(ai, bj, At, Bt) do { __builtin_amdgcn_s_setprio(1); _Pragma("unroll") for (int m = 0; m < 4; ++m) _Pragma("unroll") for (int n = 0; n < 2; ++n) _Pragma("unroll") for (int k = 0; k < 2; ++k) \
;         acc[ai][bj][m][n] = __builtin_amdgcn_mfma_f32_16x16x32_bf16(Bt[n][k], At[m][k], acc[ai][bj][m][n], 0, 0, 0); __builtin_amdgcn_s_setprio(0); } while (0)
; #define PG8_WAIT_V(n) asm volatile("s_waitcnt vmcnt(" #n ")" ::: "memory")
; #define PG8_WAIT_L(n) asm volatile("s_waitcnt lgkmcnt(" #n ")" ::: "memory")
; #define PG8_BAR __builtin_amdgcn_s_barrier()
; #define PG8_SCHED __builtin_amdgcn_sched_barrier(0)
; template <class Epi, class Sched, bool ALIGN_EPI = false, bool SP2 = false>
; __device__ __forceinline__ void gemm_phase(PG8_LAS unsigned char* lds, const Gemm g, const Sched& S, const Epi& E) {
;     ...
;             PG8_LDB(B0, 0, 0); PG8_LDB(B1, 0, 1); PG8_SCHED; PG8_LDA(At, 0, 0); PG8_STAGE(PG8_SA(1, 1), a1 + hstep, voffA);
;     ...
;             PG8_LDA(At, 1, 1); PG8_STAGE(PG8_SB(1, 0), b3, voffB); PG8_STAGE(PG8_SB(1, 1), b3 + hstep, voffB); PG8_STAGE(PG8_SA(1, 0), a3, voffA);
;             PG8_WAIT_V(8); PG8_WAIT_L(0); PG8_BAR; PG8_MMA(1, 0, At, B0); PG8_MMA(1, 1, At, B1); PG8_BAR; PG8_SCHED;
	s_add_i32 s59, s59, s93
	v_lshl_add_u64 v[136:137], v[136:137], 0, s[66:67]
	s_mov_b32 m0, s59
	ds_read_b128 v[202:205], v165 offset:49152
	ds_read_b128 v[208:211], v165 offset:50176
	ds_read_b128 v[212:215], v165 offset:51200
	ds_read_b128 v[216:219], v165 offset:52224
	ds_read_b128 v[220:223], v165 offset:53248
	ds_read_b128 v[224:227], v165 offset:54272
	ds_read_b128 v[228:231], v165 offset:55296
	ds_read_b128 v[232:235], v165 offset:56320
	global_load_lds_dwordx4 v[136:137], off
	v_lshl_add_u64 v[136:137], v[144:145], 0, s[66:67]
	s_add_i32 m0, s59, 0x2000
	s_add_i32 s59, s83, s93
	global_load_lds_dwordx4 v[136:137], off
	v_lshl_add_u64 v[136:137], v[182:183], 0, s[66:67]
	s_mov_b32 m0, s59
	s_nop 0
	global_load_lds_dwordx4 v[136:137], off
	v_lshl_add_u64 v[136:137], v[236:237], 0, s[66:67]
	s_add_i32 m0, s59, 0x2000
	s_nop 0
	global_load_lds_dwordx4 v[136:137], off
	v_lshl_add_u64 v[136:137], v[238:239], 0, s[66:67]
	s_mov_b32 m0, s73
	s_nop 0
	global_load_lds_dwordx4 v[136:137], off
	v_lshl_add_u64 v[136:137], v[240:241], 0, s[66:67]
	s_mov_b32 m0, s50
	s_nop 0
	global_load_lds_dwordx4 v[136:137], off
	s_waitcnt vmcnt(8)
	s_waitcnt lgkmcnt(0)
	s_barrier
	s_setprio 1
	s_waitcnt lgkmcnt(0)
	v_mfma_f32_16x16x32_bf16 v[62:65], v[148:151], v[202:205], v[62:65]
	v_mfma_f32_16x16x32_bf16 v[58:61], v[156:159], v[202:205], v[58:61]
	v_mfma_f32_16x16x32_bf16 v[46:49], v[148:151], v[212:215], v[46:49]
	v_mfma_f32_16x16x32_bf16 v[42:45], v[156:159], v[212:215], v[42:45]
	v_mfma_f32_16x16x32_bf16 v[30:33], v[148:151], v[220:223], v[30:33]
	v_mfma_f32_16x16x32_bf16 v[26:29], v[156:159], v[220:223], v[26:29]
	v_mfma_f32_16x16x32_bf16 v[14:17], v[148:151], v[228:231], v[14:17]
	v_mfma_f32_16x16x32_bf16 v[10:13], v[156:159], v[228:231], v[10:13]
	v_mfma_f32_16x16x32_bf16 v[62:65], v[152:155], v[208:211], v[62:65]
	v_mfma_f32_16x16x32_bf16 v[58:61], v[160:163], v[208:211], v[58:61]
	v_mfma_f32_16x16x32_bf16 v[46:49], v[152:155], v[216:219], v[46:49]
	v_mfma_f32_16x16x32_bf16 v[42:45], v[160:163], v[216:219], v[42:45]
	v_mfma_f32_16x16x32_bf16 v[30:33], v[152:155], v[224:227], v[30:33]
	v_mfma_f32_16x16x32_bf16 v[26:29], v[160:163], v[224:227], v[26:29]
	v_mfma_f32_16x16x32_bf16 v[14:17], v[152:155], v[232:235], v[14:17]
	v_mfma_f32_16x16x32_bf16 v[10:13], v[160:163], v[232:235], v[10:13]
	s_setprio 0
	s_setprio 1
	v_mfma_f32_16x16x32_bf16 v[54:57], v[166:169], v[202:205], v[54:57]
	v_mfma_f32_16x16x32_bf16 v[50:53], v[174:177], v[202:205], v[50:53]
	v_mfma_f32_16x16x32_bf16 v[38:41], v[166:169], v[212:215], v[38:41]
	v_mfma_f32_16x16x32_bf16 v[34:37], v[174:177], v[212:215], v[34:37]
	v_mfma_f32_16x16x32_bf16 v[22:25], v[166:169], v[220:223], v[22:25]
	v_mfma_f32_16x16x32_bf16 v[18:21], v[174:177], v[220:223], v[18:21]
	v_mfma_f32_16x16x32_bf16 v[6:9], v[166:169], v[228:231], v[6:9]
	v_mfma_f32_16x16x32_bf16 v[2:5], v[174:177], v[228:231], v[2:5]
	v_mfma_f32_16x16x32_bf16 v[54:57], v[170:173], v[208:211], v[54:57]
	v_mfma_f32_16x16x32_bf16 v[50:53], v[178:181], v[208:211], v[50:53]
	v_mfma_f32_16x16x32_bf16 v[38:41], v[170:173], v[216:219], v[38:41]
	v_mfma_f32_16x16x32_bf16 v[34:37], v[178:181], v[216:219], v[34:37]
	v_mfma_f32_16x16x32_bf16 v[22:25], v[170:173], v[224:227], v[22:25]
	v_mfma_f32_16x16x32_bf16 v[18:21], v[178:181], v[224:227], v[18:21]
	v_mfma_f32_16x16x32_bf16 v[6:9], v[170:173], v[232:235], v[6:9]
	v_mfma_f32_16x16x32_bf16 v[2:5], v[178:181], v[232:235], v[2:5]
	s_setprio 0
	s_barrier
	s_add_u32 s48, s48, 0x100
	s_addc_u32 s49, s49, 0
	s_add_u32 s80, s80, 0x100
	s_addc_u32 s81, s81, 0
	s_cmp_ge_u32 s82, s79
	s_mov_b32 s76, s82
	s_cbranch_scc0 .LBB0_849
	s_branch .Lkq_exit
	s_nop 0
	s_nop 0
	s_nop 0
	s_nop 0
	s_nop 0
	s_nop 0
	s_nop 0
	s_nop 0
	s_nop 0
	s_nop 0
	s_nop 0
	s_nop 0
.LBB0_849:
	s_add_i32 s82, s76, 2
	s_add_u32 s83, s48, 0x80
	s_addc_u32 s77, s49, 0
	s_add_i32 s59, 0, 0x10000
	s_cmp_eq_u32 s72, s76
	s_cselect_b32 s77, s9, s77
	s_cselect_b32 s76, s8, s83
	v_add_u32_e32 v136, s59, v147
	s_cselect_b32 vcc_hi, s47, s81
	s_cselect_b32 vcc_lo, s46, s80
	s_add_i32 s83, 0, 0x14000
	ds_read_b128 v[148:151], v136
	ds_read_b128 v[152:155], v136 offset:1024
	ds_read_b128 v[156:159], v136 offset:2048
	ds_read_b128 v[160:163], v136 offset:3072
	v_add_u32_e32 v136, s83, v147
	ds_read_b128 v[166:169], v136
	ds_read_b128 v[170:173], v136 offset:1024
	ds_read_b128 v[174:177], v136 offset:2048
	ds_read_b128 v[178:181], v136 offset:3072
	v_lshl_add_u64 v[136:137], s[48:49], 0, v[132:133]
	s_add_i32 m0, s94, 0xc000
	ds_read_b128 v[202:205], v165
	ds_read_b128 v[208:211], v165 offset:1024
	ds_read_b128 v[212:215], v165 offset:2048
	ds_read_b128 v[216:219], v165 offset:3072
	ds_read_b128 v[220:223], v165 offset:4096
	ds_read_b128 v[224:227], v165 offset:5120
	ds_read_b128 v[228:231], v165 offset:6144
	ds_read_b128 v[232:235], v165 offset:7168
	global_load_lds_dwordx4 v[136:137], off
	v_lshl_add_u64 v[136:137], s[48:49], 0, v[134:135]
	s_add_i32 m0, s94, 0xe000
	s_nop 0
	global_load_lds_dwordx4 v[136:137], off
	s_waitcnt vmcnt(8)
	s_waitcnt lgkmcnt(0)
	s_barrier
; #define PG8_STAGE(bufoff, gbase, voff) do { _Pragma("unroll") for (int _i = 0; _i < 2; ++_i) \
;         __builtin_amdgcn_global_load_lds((const unsigned*)((const char*)(gbase) + (voff)[_i]), (PG8_LAS unsigned*)(lds + (bufoff) + ldsw + _i * 8192), 16, 0, 0); } while (0)
; #define PG8_LDA(dst, b, h) do { _Pragma("unroll") for (int m = 0; m < 4; ++m) _Pragma("unroll") for (int k = 0; k < 2; ++k) dst[m][k] = *(const PG8_LAS bf16x8*)(lds + PG8_SA(b, h) + aoff + m * 2048 + k * 1024); } while (0)
; #define PG8_MMA(ai, bj, At, Bt) do { __builtin_amdgcn_s_setprio(1); _Pragma("unroll") for (int m = 0; m < 4; ++m) _Pragma("unroll") for (int n = 0; n < 2; ++n) _Pragma("unroll") for (int k = 0; k < 2; ++k) \
;         acc[ai][bj][m][n] = __builtin_amdgcn_mfma_f32_16x16x32_bf16(Bt[n][k], At[m][k], acc[ai][bj][m][n], 0, 0, 0); __builtin_amdgcn_s_setprio(0); } while (0)
; #define PG8_WAIT_V(n) asm volatile("s_waitcnt vmcnt(" #n ")" ::: "memory")
; #define PG8_WAIT_L(n) asm volatile("s_waitcnt lgkmcnt(" #n ")" ::: "memory")
; #define PG8_BAR __builtin_amdgcn_s_barrier()
; #define PG8_SCHED __builtin_amdgcn_sched_barrier(0)
; template <class Epi, class Sched, bool ALIGN_EPI = false, bool SP2 = false>
; __device__ __forceinline__ void gemm_phase(PG8_LAS unsigned char* lds, const Gemm g, const Sched& S, const Epi& E) {
;     ...
;             PG8_WAIT_V(8); PG8_WAIT_L(0); PG8_BAR; PG8_MMA(0, 0, At, B0); PG8_MMA(0, 1, At, B1); PG8_BAR; PG8_SCHED;
;             PG8_LDA(At, 0, 1); PG8_STAGE(PG8_SB(0, 0), b2, voffB); PG8_STAGE(PG8_SB(0, 1), b2 + hstep, voffB); PG8_STAGE(PG8_SA(0, 0), a2, voffA);
;             PG8_WAIT_V(8); PG8_WAIT_L(0); PG8_BAR; PG8_MMA(1, 0, At, B0); PG8_MMA(1, 1, At, B1); PG8_BAR; PG8_SCHED;
	s_setprio 1
	s_waitcnt lgkmcnt(0)
	v_mfma_f32_16x16x32_bf16 v[126:129], v[148:151], v[202:205], v[126:129]
	v_mfma_f32_16x16x32_bf16 v[122:125], v[156:159], v[202:205], v[122:125]
	v_mfma_f32_16x16x32_bf16 v[110:113], v[148:151], v[212:215], v[110:113]
	v_mfma_f32_16x16x32_bf16 v[106:109], v[156:159], v[212:215], v[106:109]
	v_mfma_f32_16x16x32_bf16 v[94:97], v[148:151], v[220:223], v[94:97]
	v_mfma_f32_16x16x32_bf16 v[90:93], v[156:159], v[220:223], v[90:93]
	v_mfma_f32_16x16x32_bf16 v[78:81], v[148:151], v[228:231], v[78:81]
	v_mfma_f32_16x16x32_bf16 v[74:77], v[156:159], v[228:231], v[74:77]
	v_mfma_f32_16x16x32_bf16 v[126:129], v[152:155], v[208:211], v[126:129]
	v_mfma_f32_16x16x32_bf16 v[122:125], v[160:163], v[208:211], v[122:125]
	v_mfma_f32_16x16x32_bf16 v[110:113], v[152:155], v[216:219], v[110:113]
	v_mfma_f32_16x16x32_bf16 v[106:109], v[160:163], v[216:219], v[106:109]
	v_mfma_f32_16x16x32_bf16 v[94:97], v[152:155], v[224:227], v[94:97]
	v_mfma_f32_16x16x32_bf16 v[90:93], v[160:163], v[224:227], v[90:93]
	v_mfma_f32_16x16x32_bf16 v[78:81], v[152:155], v[232:235], v[78:81]
	v_mfma_f32_16x16x32_bf16 v[74:77], v[160:163], v[232:235], v[74:77]
	s_setprio 0
	s_setprio 1
	v_mfma_f32_16x16x32_bf16 v[118:121], v[166:169], v[202:205], v[118:121]
	v_mfma_f32_16x16x32_bf16 v[114:117], v[174:177], v[202:205], v[114:117]
	v_mfma_f32_16x16x32_bf16 v[102:105], v[166:169], v[212:215], v[102:105]
	v_mfma_f32_16x16x32_bf16 v[98:101], v[174:177], v[212:215], v[98:101]
	v_mfma_f32_16x16x32_bf16 v[86:89], v[166:169], v[220:223], v[86:89]
	v_mfma_f32_16x16x32_bf16 v[82:85], v[174:177], v[220:223], v[82:85]
	v_mfma_f32_16x16x32_bf16 v[70:73], v[166:169], v[228:231], v[70:73]
	v_mfma_f32_16x16x32_bf16 v[66:69], v[174:177], v[228:231], v[66:69]
	v_mfma_f32_16x16x32_bf16 v[118:121], v[170:173], v[208:211], v[118:121]
	v_mfma_f32_16x16x32_bf16 v[114:117], v[178:181], v[208:211], v[114:117]
	v_mfma_f32_16x16x32_bf16 v[102:105], v[170:173], v[216:219], v[102:105]
	v_mfma_f32_16x16x32_bf16 v[98:101], v[178:181], v[216:219], v[98:101]
	v_mfma_f32_16x16x32_bf16 v[86:89], v[170:173], v[224:227], v[86:89]
	v_mfma_f32_16x16x32_bf16 v[82:85], v[178:181], v[224:227], v[82:85]
	v_mfma_f32_16x16x32_bf16 v[70:73], v[170:173], v[232:235], v[70:73]
	v_mfma_f32_16x16x32_bf16 v[66:69], v[178:181], v[232:235], v[66:69]
	s_setprio 0
	s_barrier
	s_add_i32 s59, s59, s93
	v_lshl_add_u64 v[136:137], vcc, 0, v[0:1]
	s_mov_b32 m0, s59
	ds_read_b128 v[202:205], v165 offset:16384
	ds_read_b128 v[208:211], v165 offset:17408
	ds_read_b128 v[212:215], v165 offset:18432
	ds_read_b128 v[216:219], v165 offset:19456
	ds_read_b128 v[220:223], v165 offset:20480
	ds_read_b128 v[224:227], v165 offset:21504
	ds_read_b128 v[228:231], v165 offset:22528
	ds_read_b128 v[232:235], v165 offset:23552
	global_load_lds_dwordx4 v[136:137], off
	s_add_i32 m0, s59, 0x2000
	v_lshl_add_u64 v[144:145], vcc, 0, v[130:131]
	s_add_u32 vcc_lo, vcc_lo, s10
	s_addc_u32 vcc_hi, vcc_hi, 0
	s_add_i32 s59, s83, s93
	global_load_lds_dwordx4 v[144:145], off
	v_lshl_add_u64 v[182:183], vcc, 0, v[0:1]
	s_mov_b32 m0, s59
	v_lshl_add_u64 v[236:237], vcc, 0, v[130:131]
	global_load_lds_dwordx4 v[182:183], off
	s_add_i32 m0, s59, 0x2000
	v_lshl_add_u64 v[238:239], s[76:77], 0, v[0:1]
	global_load_lds_dwordx4 v[236:237], off
	s_mov_b32 m0, s94
	v_lshl_add_u64 v[240:241], s[76:77], 0, v[130:131]
	global_load_lds_dwordx4 v[238:239], off
	s_mov_b32 m0, s95
	s_nop 0
	global_load_lds_dwordx4 v[240:241], off
	s_waitcnt vmcnt(8)
	s_waitcnt lgkmcnt(0)
	s_barrier
	s_setprio 1
	s_waitcnt lgkmcnt(0)
	v_mfma_f32_16x16x32_bf16 v[62:65], v[148:151], v[202:205], v[62:65]
	v_mfma_f32_16x16x32_bf16 v[58:61], v[156:159], v[202:205], v[58:61]
	v_mfma_f32_16x16x32_bf16 v[46:49], v[148:151], v[212:215], v[46:49]
	v_mfma_f32_16x16x32_bf16 v[42:45], v[156:159], v[212:215], v[42:45]
	v_mfma_f32_16x16x32_bf16 v[30:33], v[148:151], v[220:223], v[30:33]
	v_mfma_f32_16x16x32_bf16 v[26:29], v[156:159], v[220:223], v[26:29]
	v_mfma_f32_16x16x32_bf16 v[14:17], v[148:151], v[228:231], v[14:17]
	v_mfma_f32_16x16x32_bf16 v[10:13], v[156:159], v[228:231], v[10:13]
	v_mfma_f32_16x16x32_bf16 v[62:65], v[152:155], v[208:211], v[62:65]
	v_mfma_f32_16x16x32_bf16 v[58:61], v[160:163], v[208:211], v[58:61]
	v_mfma_f32_16x16x32_bf16 v[46:49], v[152:155], v[216:219], v[46:49]
	v_mfma_f32_16x16x32_bf16 v[42:45], v[160:163], v[216:219], v[42:45]
	v_mfma_f32_16x16x32_bf16 v[30:33], v[152:155], v[224:227], v[30:33]
	v_mfma_f32_16x16x32_bf16 v[26:29], v[160:163], v[224:227], v[26:29]
	v_mfma_f32_16x16x32_bf16 v[14:17], v[152:155], v[232:235], v[14:17]
	v_mfma_f32_16x16x32_bf16 v[10:13], v[160:163], v[232:235], v[10:13]
	s_setprio 0
	s_setprio 1
	v_mfma_f32_16x16x32_bf16 v[54:57], v[166:169], v[202:205], v[54:57]
	v_mfma_f32_16x16x32_bf16 v[50:53], v[174:177], v[202:205], v[50:53]
	v_mfma_f32_16x16x32_bf16 v[38:41], v[166:169], v[212:215], v[38:41]
	v_mfma_f32_16x16x32_bf16 v[34:37], v[174:177], v[212:215], v[34:37]
	v_mfma_f32_16x16x32_bf16 v[22:25], v[166:169], v[220:223], v[22:25]
	v_mfma_f32_16x16x32_bf16 v[18:21], v[174:177], v[220:223], v[18:21]
	v_mfma_f32_16x16x32_bf16 v[6:9], v[166:169], v[228:231], v[6:9]
	v_mfma_f32_16x16x32_bf16 v[2:5], v[174:177], v[228:231], v[2:5]
	v_mfma_f32_16x16x32_bf16 v[54:57], v[170:173], v[208:211], v[54:57]
	v_mfma_f32_16x16x32_bf16 v[50:53], v[178:181], v[208:211], v[50:53]
	v_mfma_f32_16x16x32_bf16 v[38:41], v[170:173], v[216:219], v[38:41]
	v_mfma_f32_16x16x32_bf16 v[34:37], v[178:181], v[216:219], v[34:37]
	v_mfma_f32_16x16x32_bf16 v[22:25], v[170:173], v[224:227], v[22:25]
	v_mfma_f32_16x16x32_bf16 v[18:21], v[178:181], v[224:227], v[18:21]
	v_mfma_f32_16x16x32_bf16 v[6:9], v[170:173], v[232:235], v[6:9]
	v_mfma_f32_16x16x32_bf16 v[2:5], v[178:181], v[232:235], v[2:5]
	s_setprio 0
	s_barrier
; #define PG8_STAGE(bufoff, gbase, voff) do { _Pragma("unroll") for (int _i = 0; _i < 2; ++_i) \
;         __builtin_amdgcn_global_load_lds((const unsigned*)((const char*)(gbase) + (voff)[_i]), (PG8_LAS unsigned*)(lds + (bufoff) + ldsw + _i * 8192), 16, 0, 0); } while (0)
; #define PG8_LDA(dst, b, h) do { _Pragma("unroll") for (int m = 0; m < 4; ++m) _Pragma("unroll") for (int k = 0; k < 2; ++k) dst[m][k] = *(const PG8_LAS bf16x8*)(lds + PG8_SA(b, h) + aoff + m * 2048 + k * 1024); } while (0)
; #define PG8_LDB(dst, b, h) do { _Pragma("unroll") for (int n = 0; n < 2; ++n) _Pragma("unroll") for (int k = 0; k < 2; ++k) dst[n][k] = *(const PG8_LAS bf16x8*)(lds + PG8_SB(b, h) + boff + n * 2048 + k * 1024); } while (0)
; #define PG8_MMA(ai, bj, At, Bt) do { __builtin_amdgcn_s_setprio(1); _Pragma("unroll") for (int m = 0; m < 4; ++m) _Pragma("unroll") for (int n = 0; n < 2; ++n) _Pragma("unroll") for (int k = 0; k < 2; ++k) \
;         acc[ai][bj][m][n] = __builtin_amdgcn_mfma_f32_16x16x32_bf16(Bt[n][k], At[m][k], acc[ai][bj][m][n], 0, 0, 0); __builtin_amdgcn_s_setprio(0); } while (0)
; #define PG8_WAIT_V(n) asm volatile("s_waitcnt vmcnt(" #n ")" ::: "memory")
; #define PG8_WAIT_L(n) asm volatile("s_waitcnt lgkmcnt(" #n ")" ::: "memory")
; #define PG8_BAR __builtin_amdgcn_s_barrier()
; #define PG8_SCHED __builtin_amdgcn_sched_barrier(0)
; template <class Epi, class Sched, bool ALIGN_EPI = false, bool SP2 = false>
; __device__ __forceinline__ void gemm_phase(PG8_LAS unsigned char* lds, const Gemm g, const Sched& S, const Epi& E) {
;     ...
;             PG8_LDB(B0, 1, 0); PG8_LDB(B1, 1, 1); PG8_SCHED; PG8_LDA(At, 1, 0); PG8_STAGE(PG8_SA(0, 1), a2 + hstep, voffA);
;             PG8_WAIT_V(8); PG8_WAIT_L(0); PG8_BAR; PG8_MMA(0, 0, At, B0); PG8_MMA(0, 1, At, B1); PG8_BAR; PG8_SCHED;
	s_add_i32 s59, 0, 0x18000
	s_add_i32 s83, 0, 0x1c000
	v_add_u32_e32 v160, s59, v147
	v_add_u32_e32 v178, s83, v147
	ds_read_b128 v[148:151], v160
	ds_read_b128 v[152:155], v160 offset:1024
	ds_read_b128 v[156:159], v160 offset:2048
	ds_read_b128 v[160:163], v160 offset:3072
	ds_read_b128 v[166:169], v178
	ds_read_b128 v[170:173], v178 offset:1024
	ds_read_b128 v[174:177], v178 offset:2048
	ds_read_b128 v[178:181], v178 offset:3072
	s_add_u32 s76, s76, s10
	s_addc_u32 s77, s77, 0
	s_mov_b32 m0, s84
	v_lshl_add_u64 v[242:243], s[76:77], 0, v[0:1]
	ds_read_b128 v[202:205], v165 offset:32768
	ds_read_b128 v[208:211], v165 offset:33792
	ds_read_b128 v[212:215], v165 offset:34816
	ds_read_b128 v[216:219], v165 offset:35840
	ds_read_b128 v[220:223], v165 offset:36864
	ds_read_b128 v[224:227], v165 offset:37888
	ds_read_b128 v[228:231], v165 offset:38912
	ds_read_b128 v[232:235], v165 offset:39936
	global_load_lds_dwordx4 v[242:243], off
	v_lshl_add_u64 v[242:243], s[76:77], 0, v[130:131]
	s_mov_b32 m0, s74
	s_nop 0
	global_load_lds_dwordx4 v[242:243], off
	s_waitcnt vmcnt(8)
	s_waitcnt lgkmcnt(0)
	s_barrier
	s_setprio 1
	s_waitcnt lgkmcnt(0)
	v_mfma_f32_16x16x32_bf16 v[126:129], v[148:151], v[202:205], v[126:129]
	v_mfma_f32_16x16x32_bf16 v[122:125], v[156:159], v[202:205], v[122:125]
	v_mfma_f32_16x16x32_bf16 v[110:113], v[148:151], v[212:215], v[110:113]
	v_mfma_f32_16x16x32_bf16 v[106:109], v[156:159], v[212:215], v[106:109]
	v_mfma_f32_16x16x32_bf16 v[94:97], v[148:151], v[220:223], v[94:97]
	v_mfma_f32_16x16x32_bf16 v[90:93], v[156:159], v[220:223], v[90:93]
	v_mfma_f32_16x16x32_bf16 v[78:81], v[148:151], v[228:231], v[78:81]
	v_mfma_f32_16x16x32_bf16 v[74:77], v[156:159], v[228:231], v[74:77]
	v_mfma_f32_16x16x32_bf16 v[126:129], v[152:155], v[208:211], v[126:129]
	v_mfma_f32_16x16x32_bf16 v[122:125], v[160:163], v[208:211], v[122:125]
	v_mfma_f32_16x16x32_bf16 v[110:113], v[152:155], v[216:219], v[110:113]
	v_mfma_f32_16x16x32_bf16 v[106:109], v[160:163], v[216:219], v[106:109]
	v_mfma_f32_16x16x32_bf16 v[94:97], v[152:155], v[224:227], v[94:97]
	v_mfma_f32_16x16x32_bf16 v[90:93], v[160:163], v[224:227], v[90:93]
	v_mfma_f32_16x16x32_bf16 v[78:81], v[152:155], v[232:235], v[78:81]
	v_mfma_f32_16x16x32_bf16 v[74:77], v[160:163], v[232:235], v[74:77]
	s_setprio 0
	s_setprio 1
	v_mfma_f32_16x16x32_bf16 v[118:121], v[166:169], v[202:205], v[118:121]
	v_mfma_f32_16x16x32_bf16 v[114:117], v[174:177], v[202:205], v[114:117]
	v_mfma_f32_16x16x32_bf16 v[102:105], v[166:169], v[212:215], v[102:105]
	v_mfma_f32_16x16x32_bf16 v[98:101], v[174:177], v[212:215], v[98:101]
	v_mfma_f32_16x16x32_bf16 v[86:89], v[166:169], v[220:223], v[86:89]
	v_mfma_f32_16x16x32_bf16 v[82:85], v[174:177], v[220:223], v[82:85]
	v_mfma_f32_16x16x32_bf16 v[70:73], v[166:169], v[228:231], v[70:73]
	v_mfma_f32_16x16x32_bf16 v[66:69], v[174:177], v[228:231], v[66:69]
	v_mfma_f32_16x16x32_bf16 v[118:121], v[170:173], v[208:211], v[118:121]
	v_mfma_f32_16x16x32_bf16 v[114:117], v[178:181], v[208:211], v[114:117]
	v_mfma_f32_16x16x32_bf16 v[102:105], v[170:173], v[216:219], v[102:105]
	v_mfma_f32_16x16x32_bf16 v[98:101], v[178:181], v[216:219], v[98:101]
	v_mfma_f32_16x16x32_bf16 v[86:89], v[170:173], v[224:227], v[86:89]
	v_mfma_f32_16x16x32_bf16 v[82:85], v[178:181], v[224:227], v[82:85]
	v_mfma_f32_16x16x32_bf16 v[70:73], v[170:173], v[232:235], v[70:73]
	v_mfma_f32_16x16x32_bf16 v[66:69], v[178:181], v[232:235], v[66:69]
	s_setprio 0
	s_barrier
; #define PG8_STAGE(bufoff, gbase, voff) do { _Pragma("unroll") for (int _i = 0; _i < 2; ++_i) \
;         __builtin_amdgcn_global_load_lds((const unsigned*)((const char*)(gbase) + (voff)[_i]), (PG8_LAS unsigned*)(lds + (bufoff) + ldsw + _i * 8192), 16, 0, 0); } while (0)
; #define PG8_LDA(dst, b, h) do { _Pragma("unroll") for (int m = 0; m < 4; ++m) _Pragma("unroll") for (int k = 0; k < 2; ++k) dst[m][k] = *(const PG8_LAS bf16x8*)(lds + PG8_SA(b, h) + aoff + m * 2048 + k * 1024); } while (0)
; #define PG8_MMA(ai, bj, At, Bt) do { __builtin_amdgcn_s_setprio(1); _Pragma("unroll") for (int m = 0; m < 4; ++m) _Pragma("unroll") for (int n = 0; n < 2; ++n) _Pragma("unroll") for (int k = 0; k < 2; ++k) \
;         acc[ai][bj][m][n] = __builtin_amdgcn_mfma_f32_16x16x32_bf16(Bt[n][k], At[m][k], acc[ai][bj][m][n], 0, 0, 0); __builtin_amdgcn_s_setprio(0); } while (0)
; #define PG8_WAIT_V(n) asm volatile("s_waitcnt vmcnt(" #n ")" ::: "memory")
; #define PG8_WAIT_L(n) asm volatile("s_waitcnt lgkmcnt(" #n ")" ::: "memory")
; #define PG8_BAR __builtin_amdgcn_s_barrier()
; #define PG8_SCHED __builtin_amdgcn_sched_barrier(0)
; template <class Epi, class Sched, bool ALIGN_EPI = false, bool SP2 = false>
; __device__ __forceinline__ void gemm_phase(PG8_LAS unsigned char* lds, const Gemm g, const Sched& S, const Epi& E) {
;     ...
;         for (int t = 0; t < nt; t += 2) {
;     ...
;             PG8_LDA(At, 1, 1); PG8_STAGE(PG8_SB(1, 0), b3, voffB); PG8_STAGE(PG8_SB(1, 1), b3 + hstep, voffB); PG8_STAGE(PG8_SA(1, 0), a3, voffA);
;             PG8_WAIT_V(8); PG8_WAIT_L(0); PG8_BAR; PG8_MMA(1, 0, At, B0); PG8_MMA(1, 1, At, B1); PG8_BAR; PG8_SCHED;
	s_add_i32 s59, s59, s93
	v_lshl_add_u64 v[136:137], v[136:137], 0, s[66:67]
	s_mov_b32 m0, s59
	ds_read_b128 v[202:205], v165 offset:49152
	ds_read_b128 v[208:211], v165 offset:50176
	ds_read_b128 v[212:215], v165 offset:51200
	ds_read_b128 v[216:219], v165 offset:52224
	ds_read_b128 v[220:223], v165 offset:53248
	ds_read_b128 v[224:227], v165 offset:54272
	ds_read_b128 v[228:231], v165 offset:55296
	ds_read_b128 v[232:235], v165 offset:56320
	global_load_lds_dwordx4 v[136:137], off
	v_lshl_add_u64 v[136:137], v[144:145], 0, s[66:67]
	s_add_i32 m0, s59, 0x2000
	s_add_i32 s59, s83, s93
	global_load_lds_dwordx4 v[136:137], off
	v_lshl_add_u64 v[136:137], v[182:183], 0, s[66:67]
	s_mov_b32 m0, s59
	s_nop 0
	global_load_lds_dwordx4 v[136:137], off
	v_lshl_add_u64 v[136:137], v[236:237], 0, s[66:67]
	s_add_i32 m0, s59, 0x2000
	s_nop 0
	global_load_lds_dwordx4 v[136:137], off
	v_lshl_add_u64 v[136:137], v[238:239], 0, s[66:67]
	s_mov_b32 m0, s73
	s_nop 0
	global_load_lds_dwordx4 v[136:137], off
	v_lshl_add_u64 v[136:137], v[240:241], 0, s[66:67]
	s_mov_b32 m0, s50
	s_nop 0
	global_load_lds_dwordx4 v[136:137], off
	s_waitcnt vmcnt(8)
	s_waitcnt lgkmcnt(0)
	s_barrier
	s_setprio 1
	s_waitcnt lgkmcnt(0)
	v_mfma_f32_16x16x32_bf16 v[62:65], v[148:151], v[202:205], v[62:65]
	v_mfma_f32_16x16x32_bf16 v[58:61], v[156:159], v[202:205], v[58:61]
	v_mfma_f32_16x16x32_bf16 v[46:49], v[148:151], v[212:215], v[46:49]
	v_mfma_f32_16x16x32_bf16 v[42:45], v[156:159], v[212:215], v[42:45]
	v_mfma_f32_16x16x32_bf16 v[30:33], v[148:151], v[220:223], v[30:33]
	v_mfma_f32_16x16x32_bf16 v[26:29], v[156:159], v[220:223], v[26:29]
	v_mfma_f32_16x16x32_bf16 v[14:17], v[148:151], v[228:231], v[14:17]
	v_mfma_f32_16x16x32_bf16 v[10:13], v[156:159], v[228:231], v[10:13]
	v_mfma_f32_16x16x32_bf16 v[62:65], v[152:155], v[208:211], v[62:65]
	v_mfma_f32_16x16x32_bf16 v[58:61], v[160:163], v[208:211], v[58:61]
	v_mfma_f32_16x16x32_bf16 v[46:49], v[152:155], v[216:219], v[46:49]
	v_mfma_f32_16x16x32_bf16 v[42:45], v[160:163], v[216:219], v[42:45]
	v_mfma_f32_16x16x32_bf16 v[30:33], v[152:155], v[224:227], v[30:33]
	v_mfma_f32_16x16x32_bf16 v[26:29], v[160:163], v[224:227], v[26:29]
	v_mfma_f32_16x16x32_bf16 v[14:17], v[152:155], v[232:235], v[14:17]
	v_mfma_f32_16x16x32_bf16 v[10:13], v[160:163], v[232:235], v[10:13]
	s_setprio 0
	s_setprio 1
	v_mfma_f32_16x16x32_bf16 v[54:57], v[166:169], v[202:205], v[54:57]
	v_mfma_f32_16x16x32_bf16 v[50:53], v[174:177], v[202:205], v[50:53]
	v_mfma_f32_16x16x32_bf16 v[38:41], v[166:169], v[212:215], v[38:41]
	v_mfma_f32_16x16x32_bf16 v[34:37], v[174:177], v[212:215], v[34:37]
	v_mfma_f32_16x16x32_bf16 v[22:25], v[166:169], v[220:223], v[22:25]
	v_mfma_f32_16x16x32_bf16 v[18:21], v[174:177], v[220:223], v[18:21]
	v_mfma_f32_16x16x32_bf16 v[6:9], v[166:169], v[228:231], v[6:9]
	v_mfma_f32_16x16x32_bf16 v[2:5], v[174:177], v[228:231], v[2:5]
	v_mfma_f32_16x16x32_bf16 v[54:57], v[170:173], v[208:211], v[54:57]
	v_mfma_f32_16x16x32_bf16 v[50:53], v[178:181], v[208:211], v[50:53]
	v_mfma_f32_16x16x32_bf16 v[38:41], v[170:173], v[216:219], v[38:41]
	v_mfma_f32_16x16x32_bf16 v[34:37], v[178:181], v[216:219], v[34:37]
	v_mfma_f32_16x16x32_bf16 v[22:25], v[170:173], v[224:227], v[22:25]
	v_mfma_f32_16x16x32_bf16 v[18:21], v[178:181], v[224:227], v[18:21]
	v_mfma_f32_16x16x32_bf16 v[6:9], v[170:173], v[232:235], v[6:9]
	v_mfma_f32_16x16x32_bf16 v[2:5], v[178:181], v[232:235], v[2:5]
	s_setprio 0
	s_barrier
	s_add_u32 s48, s48, 0x100
	s_addc_u32 s49, s49, 0
	s_add_u32 s80, s80, 0x100
	s_addc_u32 s81, s81, 0
	s_cmp_ge_u32 s82, s79
	s_mov_b32 s76, s82
	s_cbranch_scc0 .LBB0_849
	s_branch .Lkq_exit
	s_nop 0
	s_nop 0
	s_nop 0
	s_nop 0
	s_nop 0
	s_nop 0
	s_nop 0
	s_nop 0
	s_nop 0
	s_nop 0
	s_nop 0
	s_nop 0
